# v65 + EpiRes residual loads two row-blocks ahead (stacked)
# baseline (speedup 1.0000x reference)
; #define EPI_IT_ROW(it) EPI_ROW((it) >> 2, (it) & 3)
; #define EPI_PACK8(v0, v1) (u32x4){pk2((v0)[0], (v0)[1]), pk2((v0)[2], (v0)[3]), pk2((v1)[0], (v1)[1]), pk2((v1)[2], (v1)[3])}
;     __device__ __forceinline__ void operator()(AccRef acc, const Unit& u, int wr, int wc, int fr, int fq) const {
;     ...
;         f32x4 xc[2][2], xn[2][2];
; #pragma unroll
;         for (int bj = 0; bj < 2; ++bj) { const size_t p = (size_t)EPI_IT_ROW(0) * DM + EPI_COL(bj); xc[bj][0] = *(const f32x4*)(xin + p); xc[bj][1] = *(const f32x4*)(xin + p + 4); }
; #pragma unroll
;         for (int it = 0; it < 8; ++it) { const int ai = it >> 2, m = it & 3, row = EPI_IT_ROW(it);
;             if (it + 1 < 8) {
; #pragma unroll
;                 for (int bj = 0; bj < 2; ++bj) { const size_t p = (size_t)EPI_IT_ROW(it + 1) * DM + EPI_COL(bj); xn[bj][0] = *(const f32x4*)(xin + p); xn[bj][1] = *(const f32x4*)(xin + p + 4); } }
;             float q = 0.f;
; #pragma unroll
;             for (int bj = 0; bj < 2; ++bj) { const size_t p = (size_t)row * DM + EPI_COL(bj);
;                 const f32x4 x0 = xc[bj][0] + acc[ai][bj][m][0], x1 = xc[bj][1] + acc[ai][bj][m][1];
;                 __builtin_nontemporal_store(x0, (f32x4*)(xout + p)); __builtin_nontemporal_store(x1, (f32x4*)(xout + p + 4));
;                 *(u32x4*)(xb + p) = EPI_PACK8(x0, x1);
;                 q += EPI_SQ8(x0, x1); }
;             q += __shfl_xor(q, 16); q += __shfl_xor(q, 32);
;             if (fq == 0) atomicAdd(ssout + row, q);
; #pragma unroll
;             for (int bj = 0; bj < 2; ++bj) { xc[bj][0] = xn[bj][0]; xc[bj][1] = xn[bj][1]; } }
.LBB0_460:
	s_lshl_b32 s1, s34, 8
	v_mov_b32_e32 v128, v171
	v_mov_b32_e32 v168, v170
	s_add_i32 s1, s1, s63
	s_lshl_b32 s0, s0, 8
	s_or_b32 s0, s0, s64
	v_add_u32_e32 v164, s1, v128
	v_ashrrev_i32_e32 v165, 31, v164
	v_lshl_add_u32 v162, v168, 3, s0
	v_lshlrev_b64 v[128:129], 12, v[164:165]
	v_ashrrev_i32_e32 v163, 31, v162
	v_lshl_add_u64 v[128:129], s[16:17], 0, v[128:129]
	v_lshlrev_b64 v[130:131], 2, v[162:163]
	v_add_u32_e32 v160, 0x80, v162
	v_lshl_add_u64 v[132:133], v[128:129], 0, v[130:131]
	v_ashrrev_i32_e32 v161, 31, v160
	global_load_dwordx4 v[180:183], v[132:133], off offset:16
	global_load_dwordx4 v[184:187], v[132:133], off
	v_lshlrev_b64 v[132:133], 2, v[160:161]
	v_lshl_add_u64 v[128:129], v[128:129], 0, v[132:133]
	global_load_dwordx4 v[188:191], v[128:129], off
	global_load_dwordx4 v[192:195], v[128:129], off offset:16
	v_add_u32_e32 v166, 16, v164
	v_ashrrev_i32_e32 v167, 31, v166
	v_lshlrev_b64 v[128:129], 12, v[166:167]
	v_lshl_add_u64 v[128:129], s[16:17], 0, v[128:129]
	v_lshl_add_u64 v[130:131], v[128:129], 0, v[130:131]
	v_lshl_add_u64 v[132:133], v[128:129], 0, v[132:133]
	global_load_dwordx4 v[136:139], v[130:131], off offset:16
	global_load_dwordx4 v[140:143], v[130:131], off
	s_nop 0
	global_load_dwordx4 v[128:131], v[132:133], off offset:16
	s_nop 0
	global_load_dwordx4 v[132:135], v[132:133], off
	v_add_u32_e32 v244, 32, v164
	v_ashrrev_i32_e32 v245, 31, v244
	v_lshlrev_b64 v[246:247], 12, v[244:245]
	v_lshl_add_u64 v[246:247], s[16:17], 0, v[246:247]
	v_lshl_add_u64 v[248:249], v[162:163], 2, v[246:247]
	v_lshl_add_u64 v[250:251], v[160:161], 2, v[246:247]
	global_load_dwordx4 v[206:209], v[248:249], off offset:16
	global_load_dwordx4 v[210:213], v[248:249], off
	global_load_dwordx4 v[214:217], v[250:251], off offset:16
	global_load_dwordx4 v[218:221], v[250:251], off
	v_add_u32_e32 v244, 48, v164
	v_ashrrev_i32_e32 v245, 31, v244
	v_lshlrev_b64 v[246:247], 12, v[244:245]
	v_lshl_add_u64 v[246:247], s[16:17], 0, v[246:247]
	v_lshl_add_u64 v[248:249], v[162:163], 2, v[246:247]
	v_lshl_add_u64 v[250:251], v[160:161], 2, v[246:247]
	global_load_dwordx4 v[228:231], v[248:249], off offset:16
	global_load_dwordx4 v[232:235], v[248:249], off
	global_load_dwordx4 v[236:239], v[250:251], off offset:16
	global_load_dwordx4 v[240:243], v[250:251], off
	v_and_b32_e32 v178, 64, v177
	v_xor_b32_e32 v169, 16, v177
	v_add_u32_e32 v178, 64, v178
	v_cmp_lt_i32_e64 s[0:1], v169, v178
	v_xor_b32_e32 v179, 32, v177
	v_cmp_eq_u32_e32 vcc, 0, v168
	v_cndmask_b32_e64 v168, v177, v169, s[0:1]
	v_cmp_lt_i32_e64 s[0:1], v179, v178
	v_lshlrev_b32_e32 v178, 2, v168
	v_lshlrev_b64 v[168:169], 10, v[164:165]
	v_lshl_add_u64 v[196:197], v[168:169], 0, v[162:163]
	v_lshl_add_u64 v[198:199], v[196:197], 2, s[48:49]
	v_cndmask_b32_e64 v179, v177, v179, s[0:1]
	v_lshl_add_u64 v[168:169], v[168:169], 0, v[160:161]
	v_lshl_add_u64 v[196:197], v[196:197], 1, s[24:25]
	v_lshl_add_u64 v[200:201], v[168:169], 2, s[48:49]
	v_lshlrev_b32_e32 v179, 2, v179
	s_waitcnt vmcnt(8)
	v_pk_add_f32 v[122:123], v[122:123], v[182:183]
	v_pk_add_f32 v[126:127], v[126:127], v[186:187]
	v_pk_add_f32 v[124:125], v[124:125], v[184:185]
	v_pk_add_f32 v[118:119], v[118:119], v[190:191]
	v_pk_add_f32 v[116:117], v[116:117], v[188:189]
	v_pk_add_f32 v[120:121], v[120:121], v[180:181]
	v_pk_add_f32 v[180:181], v[112:113], v[192:193]
	global_store_dwordx4 v[198:199], v[124:127], off nt
	global_store_dwordx4 v[198:199], v[120:123], off offset:16 nt
	v_cvt_pk_bf16_f32 v112, v124, v125
	v_cvt_pk_bf16_f32 v113, v126, v127
	v_mul_f32_e32 v185, v117, v117
	v_mul_f32_e32 v125, v125, v125
	v_mul_f32_e32 v127, v127, v127
	v_mul_f32_e32 v186, v119, v119
	v_pk_add_f32 v[182:183], v[114:115], v[194:195]
	v_cvt_pk_bf16_f32 v114, v120, v121
	v_cvt_pk_bf16_f32 v115, v122, v123
	v_mul_f32_e32 v121, v121, v121
	v_mul_f32_e32 v123, v123, v123
	v_mul_f32_e32 v187, v181, v181
	v_fmac_f32_e32 v125, v124, v124
	v_fmac_f32_e32 v127, v126, v126
	v_fmac_f32_e32 v185, v116, v116
	v_fmac_f32_e32 v186, v118, v118
	v_mul_f32_e32 v188, v183, v183
	v_fmac_f32_e32 v121, v120, v120
	v_fmac_f32_e32 v123, v122, v122
	v_fmac_f32_e32 v187, v180, v180
	v_add_f32_e32 v120, v125, v127
	v_add_f32_e32 v122, v185, v186
	v_fmac_f32_e32 v188, v182, v182
	v_add_f32_e32 v120, v120, v121
	v_add_f32_e32 v121, v122, v187
	v_add_f32_e32 v120, v123, v120
	v_add_f32_e32 v121, v188, v121
	v_add_f32_e32 v120, v120, v121
	v_mov_b32_e32 v121, v120
	s_nop 1
	v_permlane16_swap_b32_e32 v121, v120
	global_store_dwordx4 v[196:197], v[112:115], off
	global_store_dwordx4 v[200:201], v[116:119], off nt
	global_store_dwordx4 v[200:201], v[180:183], off offset:16 nt
	v_lshl_add_u64 v[114:115], v[168:169], 1, s[24:25]
	v_cvt_pk_bf16_f32 v184, v116, v117
	v_cvt_pk_bf16_f32 v185, v118, v119
	s_waitcnt lgkmcnt(0)
	v_add_f32_e32 v112, v120, v121
	v_mov_b32_e32 v113, v112
	s_nop 1
	v_permlane32_swap_b32_e32 v113, v112
	v_cvt_pk_bf16_f32 v186, v180, v181
	v_cvt_pk_bf16_f32 v187, v182, v183
	global_store_dwordx4 v[114:115], v[184:187], off
	s_and_saveexec_b64 s[0:1], vcc
	s_cbranch_execz .LBB0_462
	v_lshl_add_u64 v[114:115], v[164:165], 2, s[10:11]
	s_waitcnt lgkmcnt(0)
	v_add_f32_e32 v112, v112, v113
	global_atomic_add_f32 v[114:115], v112, off
; #define EPI_IT_ROW(it) EPI_ROW((it) >> 2, (it) & 3)
; #define EPI_PACK8(v0, v1) (u32x4){pk2((v0)[0], (v0)[1]), pk2((v0)[2], (v0)[3]), pk2((v1)[0], (v1)[1]), pk2((v1)[2], (v1)[3])}
;     __device__ __forceinline__ void operator()(AccRef acc, const Unit& u, int wr, int wc, int fr, int fq) const {
;     ...
;         for (int bj = 0; bj < 2; ++bj) { const size_t p = (size_t)EPI_IT_ROW(0) * DM + EPI_COL(bj); xc[bj][0] = *(const f32x4*)(xin + p); xc[bj][1] = *(const f32x4*)(xin + p + 4); }
; #pragma unroll
;         for (int it = 0; it < 8; ++it) { const int ai = it >> 2, m = it & 3, row = EPI_IT_ROW(it);
;             if (it + 1 < 8) {
; #pragma unroll
;                 for (int bj = 0; bj < 2; ++bj) { const size_t p = (size_t)EPI_IT_ROW(it + 1) * DM + EPI_COL(bj); xn[bj][0] = *(const f32x4*)(xin + p); xn[bj][1] = *(const f32x4*)(xin + p + 4); } }
;             float q = 0.f;
; #pragma unroll
;             for (int bj = 0; bj < 2; ++bj) { const size_t p = (size_t)row * DM + EPI_COL(bj);
;                 const f32x4 x0 = xc[bj][0] + acc[ai][bj][m][0], x1 = xc[bj][1] + acc[ai][bj][m][1];
;                 __builtin_nontemporal_store(x0, (f32x4*)(xout + p)); __builtin_nontemporal_store(x1, (f32x4*)(xout + p + 4));
;                 *(u32x4*)(xb + p) = EPI_PACK8(x0, x1);
;                 q += EPI_SQ8(x0, x1); }
;             q += __shfl_xor(q, 16); q += __shfl_xor(q, 32);
;             if (fq == 0) atomicAdd(ssout + row, q);
; #pragma unroll
;             for (int bj = 0; bj < 2; ++bj) { xc[bj][0] = xn[bj][0]; xc[bj][1] = xn[bj][1]; } }
.LBB0_462:
	s_or_b64 exec, exec, s[0:1]
	v_add_u32_e32 v168, 32, v164
	v_ashrrev_i32_e32 v169, 31, v168
	s_waitcnt lgkmcnt(0)
	v_lshlrev_b64 v[112:113], 12, v[168:169]
	v_lshl_add_u64 v[112:113], s[16:17], 0, v[112:113]
	v_lshl_add_u64 v[114:115], v[162:163], 2, v[112:113]
	v_lshl_add_u64 v[116:117], v[160:161], 2, v[112:113]
	s_nop 0
	s_nop 0
	v_lshlrev_b64 v[180:181], 10, v[166:167]
	v_lshl_add_u64 v[182:183], v[180:181], 0, v[162:163]
	v_pk_add_f32 v[110:111], v[110:111], v[142:143]
	v_pk_add_f32 v[108:109], v[108:109], v[140:141]
	v_pk_add_f32 v[104:105], v[104:105], v[136:137]
	v_lshl_add_u64 v[136:137], v[182:183], 2, s[48:49]
	v_pk_add_f32 v[106:107], v[106:107], v[138:139]
	global_store_dwordx4 v[136:137], v[108:111], off nt
	global_store_dwordx4 v[136:137], v[104:107], off offset:16 nt
	v_cvt_pk_bf16_f32 v136, v108, v109
	v_cvt_pk_bf16_f32 v138, v104, v105
	v_pk_add_f32 v[102:103], v[102:103], v[134:135]
	v_mul_f32_e32 v109, v109, v109
	v_fmac_f32_e32 v109, v108, v108
	v_mul_f32_e32 v108, v111, v111
	v_fmac_f32_e32 v108, v110, v110
	v_mul_f32_e32 v105, v105, v105
	v_add_f32_e32 v108, v109, v108
	v_fmac_f32_e32 v105, v104, v104
	v_add_f32_e32 v104, v108, v105
	v_mul_f32_e32 v105, v107, v107
	v_pk_add_f32 v[100:101], v[100:101], v[132:133]
	v_cvt_pk_bf16_f32 v139, v106, v107
	v_fmac_f32_e32 v105, v106, v106
	v_pk_add_f32 v[106:107], v[98:99], v[130:131]
	v_mul_f32_e32 v98, v101, v101
	v_mul_f32_e32 v99, v103, v103
	v_cvt_pk_bf16_f32 v137, v110, v111
	v_add_f32_e32 v110, v105, v104
	v_pk_add_f32 v[104:105], v[96:97], v[128:129]
	v_fmac_f32_e32 v98, v100, v100
	v_fmac_f32_e32 v99, v102, v102
	v_add_f32_e32 v98, v98, v99
	v_mul_f32_e32 v99, v105, v105
	v_fmac_f32_e32 v99, v104, v104
	v_add_f32_e32 v98, v98, v99
	v_mul_f32_e32 v99, v107, v107
	v_fmac_f32_e32 v99, v106, v106
	v_add_f32_e32 v98, v99, v98
	v_add_f32_e32 v110, v110, v98
	v_mov_b32_e32 v111, v110
	s_nop 1
	v_permlane16_swap_b32_e32 v111, v110
	v_lshl_add_u64 v[108:109], v[180:181], 0, v[160:161]
	v_lshl_add_u64 v[140:141], v[182:183], 1, s[24:25]
	v_lshl_add_u64 v[96:97], v[108:109], 2, s[48:49]
	global_store_dwordx4 v[140:141], v[136:139], off
	global_store_dwordx4 v[96:97], v[100:103], off nt
	global_store_dwordx4 v[96:97], v[104:107], off offset:16 nt
	s_waitcnt lgkmcnt(0)
	v_add_f32_e32 v96, v110, v111
	v_mov_b32_e32 v97, v96
	s_nop 1
	v_permlane32_swap_b32_e32 v97, v96
	v_cvt_pk_bf16_f32 v99, v102, v103
	v_lshl_add_u64 v[102:103], v[108:109], 1, s[24:25]
	v_cvt_pk_bf16_f32 v98, v100, v101
	v_cvt_pk_bf16_f32 v100, v104, v105
	v_cvt_pk_bf16_f32 v101, v106, v107
	global_store_dwordx4 v[102:103], v[98:101], off
	s_and_saveexec_b64 s[0:1], vcc
	s_cbranch_execz .LBB0_464
	v_lshl_add_u64 v[98:99], v[166:167], 2, s[10:11]
	s_waitcnt lgkmcnt(0)
	v_add_f32_e32 v96, v96, v97
	global_atomic_add_f32 v[98:99], v96, off
.LBB0_464:
	s_or_b64 exec, exec, s[0:1]
	s_waitcnt vmcnt(16)
	v_mov_b64_e32 v[120:121], v[206:207]
	v_mov_b64_e32 v[122:123], v[208:209]
	v_mov_b64_e32 v[124:125], v[210:211]
	v_mov_b64_e32 v[126:127], v[212:213]
	v_mov_b64_e32 v[112:113], v[214:215]
	v_mov_b64_e32 v[114:115], v[216:217]
	v_mov_b64_e32 v[116:117], v[218:219]
	v_mov_b64_e32 v[118:119], v[220:221]
	v_add_u32_e32 v244, 128, v164
	v_ashrrev_i32_e32 v245, 31, v244
	v_lshlrev_b64 v[246:247], 12, v[244:245]
	v_lshl_add_u64 v[246:247], s[16:17], 0, v[246:247]
	v_lshl_add_u64 v[248:249], v[162:163], 2, v[246:247]
	v_lshl_add_u64 v[250:251], v[160:161], 2, v[246:247]
	global_load_dwordx4 v[206:209], v[248:249], off offset:16
	global_load_dwordx4 v[210:213], v[248:249], off
	global_load_dwordx4 v[214:217], v[250:251], off offset:16
	global_load_dwordx4 v[218:221], v[250:251], off
	v_add_u32_e32 v128, 48, v164
	v_ashrrev_i32_e32 v129, 31, v128
	s_waitcnt lgkmcnt(0)
	v_lshlrev_b64 v[96:97], 12, v[128:129]
	v_lshl_add_u64 v[96:97], s[16:17], 0, v[96:97]
	v_lshl_add_u64 v[98:99], v[162:163], 2, v[96:97]
	v_lshl_add_u64 v[100:101], v[160:161], 2, v[96:97]
	s_nop 0
	s_nop 0
	v_lshlrev_b64 v[130:131], 10, v[168:169]
	v_lshl_add_u64 v[132:133], v[130:131], 0, v[162:163]
	v_pk_add_f32 v[94:95], v[94:95], v[126:127]
	v_pk_add_f32 v[92:93], v[92:93], v[124:125]
	v_pk_add_f32 v[88:89], v[88:89], v[120:121]
	v_lshl_add_u64 v[120:121], v[132:133], 2, s[48:49]
	v_pk_add_f32 v[90:91], v[90:91], v[122:123]
	global_store_dwordx4 v[120:121], v[92:95], off nt
	global_store_dwordx4 v[120:121], v[88:91], off offset:16 nt
	v_cvt_pk_bf16_f32 v120, v92, v93
	v_cvt_pk_bf16_f32 v122, v88, v89
	v_pk_add_f32 v[86:87], v[86:87], v[118:119]
	v_mul_f32_e32 v93, v93, v93
	v_fmac_f32_e32 v93, v92, v92
	v_mul_f32_e32 v92, v95, v95
	v_fmac_f32_e32 v92, v94, v94
	v_mul_f32_e32 v89, v89, v89
	v_add_f32_e32 v92, v93, v92
	v_fmac_f32_e32 v89, v88, v88
	v_add_f32_e32 v88, v92, v89
	v_mul_f32_e32 v89, v91, v91
	v_pk_add_f32 v[84:85], v[84:85], v[116:117]
	v_cvt_pk_bf16_f32 v123, v90, v91
	v_fmac_f32_e32 v89, v90, v90
	v_pk_add_f32 v[90:91], v[82:83], v[114:115]
	v_mul_f32_e32 v82, v85, v85
	v_mul_f32_e32 v83, v87, v87
	v_cvt_pk_bf16_f32 v121, v94, v95
	v_add_f32_e32 v94, v89, v88
	v_pk_add_f32 v[88:89], v[80:81], v[112:113]
	v_fmac_f32_e32 v82, v84, v84
	v_fmac_f32_e32 v83, v86, v86
	v_add_f32_e32 v82, v82, v83
	v_mul_f32_e32 v83, v89, v89
	v_fmac_f32_e32 v83, v88, v88
	v_add_f32_e32 v82, v82, v83
	v_mul_f32_e32 v83, v91, v91
	v_fmac_f32_e32 v83, v90, v90
	v_add_f32_e32 v82, v83, v82
	v_add_f32_e32 v94, v94, v82
	v_mov_b32_e32 v95, v94
	s_nop 1
	v_permlane16_swap_b32_e32 v95, v94
	v_lshl_add_u64 v[92:93], v[130:131], 0, v[160:161]
	v_lshl_add_u64 v[124:125], v[132:133], 1, s[24:25]
	v_lshl_add_u64 v[80:81], v[92:93], 2, s[48:49]
	global_store_dwordx4 v[124:125], v[120:123], off
	global_store_dwordx4 v[80:81], v[84:87], off nt
	global_store_dwordx4 v[80:81], v[88:91], off offset:16 nt
	s_waitcnt lgkmcnt(0)
	v_add_f32_e32 v80, v94, v95
	v_mov_b32_e32 v81, v80
	s_nop 1
	v_permlane32_swap_b32_e32 v81, v80
	v_cvt_pk_bf16_f32 v83, v86, v87
	v_lshl_add_u64 v[86:87], v[92:93], 1, s[24:25]
	v_cvt_pk_bf16_f32 v82, v84, v85
	v_cvt_pk_bf16_f32 v84, v88, v89
	v_cvt_pk_bf16_f32 v85, v90, v91
	global_store_dwordx4 v[86:87], v[82:85], off
	s_and_saveexec_b64 s[0:1], vcc
	s_cbranch_execz .LBB0_466
	v_lshl_add_u64 v[82:83], v[168:169], 2, s[10:11]
	s_waitcnt lgkmcnt(0)
	v_add_f32_e32 v80, v80, v81
	global_atomic_add_f32 v[82:83], v80, off
; #define EPI_IT_ROW(it) EPI_ROW((it) >> 2, (it) & 3)
; #define EPI_PACK8(v0, v1) (u32x4){pk2((v0)[0], (v0)[1]), pk2((v0)[2], (v0)[3]), pk2((v1)[0], (v1)[1]), pk2((v1)[2], (v1)[3])}
;     __device__ __forceinline__ void operator()(AccRef acc, const Unit& u, int wr, int wc, int fr, int fq) const {
;     ...
;         for (int bj = 0; bj < 2; ++bj) { const size_t p = (size_t)EPI_IT_ROW(0) * DM + EPI_COL(bj); xc[bj][0] = *(const f32x4*)(xin + p); xc[bj][1] = *(const f32x4*)(xin + p + 4); }
; #pragma unroll
;         for (int it = 0; it < 8; ++it) { const int ai = it >> 2, m = it & 3, row = EPI_IT_ROW(it);
;             if (it + 1 < 8) {
; #pragma unroll
;                 for (int bj = 0; bj < 2; ++bj) { const size_t p = (size_t)EPI_IT_ROW(it + 1) * DM + EPI_COL(bj); xn[bj][0] = *(const f32x4*)(xin + p); xn[bj][1] = *(const f32x4*)(xin + p + 4); } }
;             float q = 0.f;
; #pragma unroll
;             for (int bj = 0; bj < 2; ++bj) { const size_t p = (size_t)row * DM + EPI_COL(bj);
;                 const f32x4 x0 = xc[bj][0] + acc[ai][bj][m][0], x1 = xc[bj][1] + acc[ai][bj][m][1];
;                 __builtin_nontemporal_store(x0, (f32x4*)(xout + p)); __builtin_nontemporal_store(x1, (f32x4*)(xout + p + 4));
;                 *(u32x4*)(xb + p) = EPI_PACK8(x0, x1);
;                 q += EPI_SQ8(x0, x1); }
;             q += __shfl_xor(q, 16); q += __shfl_xor(q, 32);
;             if (fq == 0) atomicAdd(ssout + row, q);
; #pragma unroll
;             for (int bj = 0; bj < 2; ++bj) { xc[bj][0] = xn[bj][0]; xc[bj][1] = xn[bj][1]; } }
.LBB0_466:
	s_or_b64 exec, exec, s[0:1]
	s_waitcnt vmcnt(22)
	v_mov_b64_e32 v[104:105], v[228:229]
	v_mov_b64_e32 v[106:107], v[230:231]
	v_mov_b64_e32 v[108:109], v[232:233]
	v_mov_b64_e32 v[110:111], v[234:235]
	v_mov_b64_e32 v[96:97], v[236:237]
	v_mov_b64_e32 v[98:99], v[238:239]
	v_mov_b64_e32 v[100:101], v[240:241]
	v_mov_b64_e32 v[102:103], v[242:243]
	v_add_u32_e32 v244, 144, v164
	v_ashrrev_i32_e32 v245, 31, v244
	v_lshlrev_b64 v[246:247], 12, v[244:245]
	v_lshl_add_u64 v[246:247], s[16:17], 0, v[246:247]
	v_lshl_add_u64 v[248:249], v[162:163], 2, v[246:247]
	v_lshl_add_u64 v[250:251], v[160:161], 2, v[246:247]
	global_load_dwordx4 v[228:231], v[248:249], off offset:16
	global_load_dwordx4 v[232:235], v[248:249], off
	global_load_dwordx4 v[236:239], v[250:251], off offset:16
	global_load_dwordx4 v[240:243], v[250:251], off
	v_add_u32_e32 v112, 0x80, v164
	v_ashrrev_i32_e32 v113, 31, v112
	s_waitcnt lgkmcnt(0)
	v_lshlrev_b64 v[80:81], 12, v[112:113]
	v_lshl_add_u64 v[80:81], s[16:17], 0, v[80:81]
	v_lshl_add_u64 v[82:83], v[162:163], 2, v[80:81]
	v_lshl_add_u64 v[84:85], v[160:161], 2, v[80:81]
	s_nop 0
	s_nop 0
	v_lshlrev_b64 v[114:115], 10, v[128:129]
	v_lshl_add_u64 v[116:117], v[114:115], 0, v[162:163]
	v_pk_add_f32 v[78:79], v[78:79], v[110:111]
	v_pk_add_f32 v[76:77], v[76:77], v[108:109]
	v_pk_add_f32 v[72:73], v[72:73], v[104:105]
	v_lshl_add_u64 v[104:105], v[116:117], 2, s[48:49]
	v_pk_add_f32 v[74:75], v[74:75], v[106:107]
	global_store_dwordx4 v[104:105], v[76:79], off nt
	global_store_dwordx4 v[104:105], v[72:75], off offset:16 nt
	v_cvt_pk_bf16_f32 v104, v76, v77
	v_cvt_pk_bf16_f32 v106, v72, v73
	v_pk_add_f32 v[70:71], v[70:71], v[102:103]
	v_mul_f32_e32 v77, v77, v77
	v_fmac_f32_e32 v77, v76, v76
	v_mul_f32_e32 v76, v79, v79
	v_fmac_f32_e32 v76, v78, v78
	v_mul_f32_e32 v73, v73, v73
	v_add_f32_e32 v76, v77, v76
	v_fmac_f32_e32 v73, v72, v72
	v_add_f32_e32 v72, v76, v73
	v_mul_f32_e32 v73, v75, v75
	v_pk_add_f32 v[68:69], v[68:69], v[100:101]
	v_cvt_pk_bf16_f32 v107, v74, v75
	v_fmac_f32_e32 v73, v74, v74
	v_pk_add_f32 v[74:75], v[66:67], v[98:99]
	v_mul_f32_e32 v66, v69, v69
	v_mul_f32_e32 v67, v71, v71
	v_cvt_pk_bf16_f32 v105, v78, v79
	v_add_f32_e32 v78, v73, v72
	v_pk_add_f32 v[72:73], v[64:65], v[96:97]
	v_fmac_f32_e32 v66, v68, v68
	v_fmac_f32_e32 v67, v70, v70
	v_add_f32_e32 v66, v66, v67
	v_mul_f32_e32 v67, v73, v73
	v_fmac_f32_e32 v67, v72, v72
	v_add_f32_e32 v66, v66, v67
	v_mul_f32_e32 v67, v75, v75
	v_fmac_f32_e32 v67, v74, v74
	v_add_f32_e32 v66, v67, v66
	v_add_f32_e32 v78, v78, v66
	v_mov_b32_e32 v79, v78
	s_nop 1
	v_permlane16_swap_b32_e32 v79, v78
	v_lshl_add_u64 v[76:77], v[114:115], 0, v[160:161]
	v_lshl_add_u64 v[108:109], v[116:117], 1, s[24:25]
	v_lshl_add_u64 v[64:65], v[76:77], 2, s[48:49]
	global_store_dwordx4 v[108:109], v[104:107], off
	global_store_dwordx4 v[64:65], v[68:71], off nt
	global_store_dwordx4 v[64:65], v[72:75], off offset:16 nt
	s_waitcnt lgkmcnt(0)
	v_add_f32_e32 v64, v78, v79
	v_mov_b32_e32 v65, v64
	s_nop 1
	v_permlane32_swap_b32_e32 v65, v64
	v_cvt_pk_bf16_f32 v67, v70, v71
	v_lshl_add_u64 v[70:71], v[76:77], 1, s[24:25]
	v_cvt_pk_bf16_f32 v66, v68, v69
	v_cvt_pk_bf16_f32 v68, v72, v73
	v_cvt_pk_bf16_f32 v69, v74, v75
	global_store_dwordx4 v[70:71], v[66:69], off
	s_and_saveexec_b64 s[0:1], vcc
	s_cbranch_execz .LBB0_468
	v_lshl_add_u64 v[66:67], v[128:129], 2, s[10:11]
	s_waitcnt lgkmcnt(0)
	v_add_f32_e32 v64, v64, v65
	global_atomic_add_f32 v[66:67], v64, off
.LBB0_468:
	s_or_b64 exec, exec, s[0:1]
	s_waitcnt vmcnt(16)
	v_mov_b64_e32 v[88:89], v[206:207]
	v_mov_b64_e32 v[90:91], v[208:209]
	v_mov_b64_e32 v[92:93], v[210:211]
	v_mov_b64_e32 v[94:95], v[212:213]
	v_mov_b64_e32 v[80:81], v[214:215]
	v_mov_b64_e32 v[82:83], v[216:217]
	v_mov_b64_e32 v[84:85], v[218:219]
	v_mov_b64_e32 v[86:87], v[220:221]
	v_add_u32_e32 v244, 160, v164
	v_ashrrev_i32_e32 v245, 31, v244
	v_lshlrev_b64 v[246:247], 12, v[244:245]
	v_lshl_add_u64 v[246:247], s[16:17], 0, v[246:247]
	v_lshl_add_u64 v[248:249], v[162:163], 2, v[246:247]
	v_lshl_add_u64 v[250:251], v[160:161], 2, v[246:247]
	global_load_dwordx4 v[206:209], v[248:249], off offset:16
	global_load_dwordx4 v[210:213], v[248:249], off
	global_load_dwordx4 v[214:217], v[250:251], off offset:16
	global_load_dwordx4 v[218:221], v[250:251], off
	v_add_u32_e32 v96, 0x90, v164
	v_ashrrev_i32_e32 v97, 31, v96
	s_waitcnt lgkmcnt(0)
	v_lshlrev_b64 v[64:65], 12, v[96:97]
	v_lshl_add_u64 v[64:65], s[16:17], 0, v[64:65]
	v_lshl_add_u64 v[66:67], v[162:163], 2, v[64:65]
	v_lshl_add_u64 v[68:69], v[160:161], 2, v[64:65]
	s_nop 0
	s_nop 0
	v_lshlrev_b64 v[98:99], 10, v[112:113]
	v_lshl_add_u64 v[100:101], v[98:99], 0, v[162:163]
	v_pk_add_f32 v[62:63], v[62:63], v[94:95]
	v_pk_add_f32 v[60:61], v[60:61], v[92:93]
	v_pk_add_f32 v[56:57], v[56:57], v[88:89]
	v_lshl_add_u64 v[88:89], v[100:101], 2, s[48:49]
	v_pk_add_f32 v[58:59], v[58:59], v[90:91]
	global_store_dwordx4 v[88:89], v[60:63], off nt
	global_store_dwordx4 v[88:89], v[56:59], off offset:16 nt
	v_cvt_pk_bf16_f32 v88, v60, v61
	v_cvt_pk_bf16_f32 v90, v56, v57
	v_pk_add_f32 v[54:55], v[54:55], v[86:87]
	v_mul_f32_e32 v61, v61, v61
	v_fmac_f32_e32 v61, v60, v60
	v_mul_f32_e32 v60, v63, v63
	v_fmac_f32_e32 v60, v62, v62
	v_mul_f32_e32 v57, v57, v57
	v_add_f32_e32 v60, v61, v60
	v_fmac_f32_e32 v57, v56, v56
	v_add_f32_e32 v56, v60, v57
	v_mul_f32_e32 v57, v59, v59
	v_pk_add_f32 v[52:53], v[52:53], v[84:85]
	v_cvt_pk_bf16_f32 v91, v58, v59
	v_fmac_f32_e32 v57, v58, v58
	v_pk_add_f32 v[58:59], v[50:51], v[82:83]
	v_mul_f32_e32 v50, v53, v53
	v_mul_f32_e32 v51, v55, v55
	v_cvt_pk_bf16_f32 v89, v62, v63
	v_add_f32_e32 v62, v57, v56
	v_pk_add_f32 v[56:57], v[48:49], v[80:81]
	v_fmac_f32_e32 v50, v52, v52
	v_fmac_f32_e32 v51, v54, v54
	v_add_f32_e32 v50, v50, v51
	v_mul_f32_e32 v51, v57, v57
	v_fmac_f32_e32 v51, v56, v56
	v_add_f32_e32 v50, v50, v51
	v_mul_f32_e32 v51, v59, v59
	v_fmac_f32_e32 v51, v58, v58
	v_add_f32_e32 v50, v51, v50
	v_add_f32_e32 v62, v62, v50
	v_mov_b32_e32 v63, v62
	s_nop 1
	v_permlane16_swap_b32_e32 v63, v62
	v_lshl_add_u64 v[60:61], v[98:99], 0, v[160:161]
	v_lshl_add_u64 v[92:93], v[100:101], 1, s[24:25]
	v_lshl_add_u64 v[48:49], v[60:61], 2, s[48:49]
	global_store_dwordx4 v[92:93], v[88:91], off
	global_store_dwordx4 v[48:49], v[52:55], off nt
	global_store_dwordx4 v[48:49], v[56:59], off offset:16 nt
	s_waitcnt lgkmcnt(0)
	v_add_f32_e32 v48, v62, v63
	v_mov_b32_e32 v49, v48
	s_nop 1
	v_permlane32_swap_b32_e32 v49, v48
	v_cvt_pk_bf16_f32 v51, v54, v55
	v_lshl_add_u64 v[54:55], v[60:61], 1, s[24:25]
	v_cvt_pk_bf16_f32 v50, v52, v53
	v_cvt_pk_bf16_f32 v52, v56, v57
	v_cvt_pk_bf16_f32 v53, v58, v59
	global_store_dwordx4 v[54:55], v[50:53], off
	s_and_saveexec_b64 s[0:1], vcc
	s_cbranch_execz .LBB0_470
	v_lshl_add_u64 v[50:51], v[112:113], 2, s[10:11]
	s_waitcnt lgkmcnt(0)
	v_add_f32_e32 v48, v48, v49
	global_atomic_add_f32 v[50:51], v48, off
; #define EPI_IT_ROW(it) EPI_ROW((it) >> 2, (it) & 3)
; #define EPI_PACK8(v0, v1) (u32x4){pk2((v0)[0], (v0)[1]), pk2((v0)[2], (v0)[3]), pk2((v1)[0], (v1)[1]), pk2((v1)[2], (v1)[3])}
;     __device__ __forceinline__ void operator()(AccRef acc, const Unit& u, int wr, int wc, int fr, int fq) const {
;     ...
;         for (int bj = 0; bj < 2; ++bj) { const size_t p = (size_t)EPI_IT_ROW(0) * DM + EPI_COL(bj); xc[bj][0] = *(const f32x4*)(xin + p); xc[bj][1] = *(const f32x4*)(xin + p + 4); }
; #pragma unroll
;         for (int it = 0; it < 8; ++it) { const int ai = it >> 2, m = it & 3, row = EPI_IT_ROW(it);
;             if (it + 1 < 8) {
; #pragma unroll
;                 for (int bj = 0; bj < 2; ++bj) { const size_t p = (size_t)EPI_IT_ROW(it + 1) * DM + EPI_COL(bj); xn[bj][0] = *(const f32x4*)(xin + p); xn[bj][1] = *(const f32x4*)(xin + p + 4); } }
;             float q = 0.f;
; #pragma unroll
;             for (int bj = 0; bj < 2; ++bj) { const size_t p = (size_t)row * DM + EPI_COL(bj);
;                 const f32x4 x0 = xc[bj][0] + acc[ai][bj][m][0], x1 = xc[bj][1] + acc[ai][bj][m][1];
;                 __builtin_nontemporal_store(x0, (f32x4*)(xout + p)); __builtin_nontemporal_store(x1, (f32x4*)(xout + p + 4));
;                 *(u32x4*)(xb + p) = EPI_PACK8(x0, x1);
;                 q += EPI_SQ8(x0, x1); }
;             q += __shfl_xor(q, 16); q += __shfl_xor(q, 32);
;             if (fq == 0) atomicAdd(ssout + row, q);
; #pragma unroll
;             for (int bj = 0; bj < 2; ++bj) { xc[bj][0] = xn[bj][0]; xc[bj][1] = xn[bj][1]; } }
.LBB0_470:
	s_or_b64 exec, exec, s[0:1]
	s_waitcnt vmcnt(16)
	v_mov_b64_e32 v[72:73], v[228:229]
	v_mov_b64_e32 v[74:75], v[230:231]
	v_mov_b64_e32 v[76:77], v[232:233]
	v_mov_b64_e32 v[78:79], v[234:235]
	v_mov_b64_e32 v[64:65], v[236:237]
	v_mov_b64_e32 v[66:67], v[238:239]
	v_mov_b64_e32 v[68:69], v[240:241]
	v_mov_b64_e32 v[70:71], v[242:243]
	v_add_u32_e32 v244, 176, v164
	v_ashrrev_i32_e32 v245, 31, v244
	v_lshlrev_b64 v[246:247], 12, v[244:245]
	v_lshl_add_u64 v[246:247], s[16:17], 0, v[246:247]
	v_lshl_add_u64 v[248:249], v[162:163], 2, v[246:247]
	v_lshl_add_u64 v[250:251], v[160:161], 2, v[246:247]
	global_load_dwordx4 v[228:231], v[248:249], off offset:16
	global_load_dwordx4 v[232:235], v[248:249], off
	global_load_dwordx4 v[236:239], v[250:251], off offset:16
	global_load_dwordx4 v[240:243], v[250:251], off
	v_add_u32_e32 v80, 0xa0, v164
	v_ashrrev_i32_e32 v81, 31, v80
	s_waitcnt lgkmcnt(0)
	v_lshlrev_b64 v[48:49], 12, v[80:81]
	v_lshl_add_u64 v[48:49], s[16:17], 0, v[48:49]
	v_lshl_add_u64 v[50:51], v[162:163], 2, v[48:49]
	v_lshl_add_u64 v[52:53], v[160:161], 2, v[48:49]
	s_nop 0
	s_nop 0
	v_lshlrev_b64 v[82:83], 10, v[96:97]
	v_lshl_add_u64 v[84:85], v[82:83], 0, v[162:163]
	v_pk_add_f32 v[46:47], v[46:47], v[78:79]
	v_pk_add_f32 v[44:45], v[44:45], v[76:77]
	v_pk_add_f32 v[40:41], v[40:41], v[72:73]
	v_lshl_add_u64 v[72:73], v[84:85], 2, s[48:49]
	v_pk_add_f32 v[42:43], v[42:43], v[74:75]
	global_store_dwordx4 v[72:73], v[44:47], off nt
	global_store_dwordx4 v[72:73], v[40:43], off offset:16 nt
	v_cvt_pk_bf16_f32 v72, v44, v45
	v_cvt_pk_bf16_f32 v74, v40, v41
	v_pk_add_f32 v[38:39], v[38:39], v[70:71]
	v_mul_f32_e32 v45, v45, v45
	v_fmac_f32_e32 v45, v44, v44
	v_mul_f32_e32 v44, v47, v47
	v_fmac_f32_e32 v44, v46, v46
	v_mul_f32_e32 v41, v41, v41
	v_add_f32_e32 v44, v45, v44
	v_fmac_f32_e32 v41, v40, v40
	v_add_f32_e32 v40, v44, v41
	v_mul_f32_e32 v41, v43, v43
	v_pk_add_f32 v[36:37], v[36:37], v[68:69]
	v_cvt_pk_bf16_f32 v75, v42, v43
	v_fmac_f32_e32 v41, v42, v42
	v_pk_add_f32 v[42:43], v[34:35], v[66:67]
	v_mul_f32_e32 v34, v37, v37
	v_mul_f32_e32 v35, v39, v39
	v_cvt_pk_bf16_f32 v73, v46, v47
	v_add_f32_e32 v46, v41, v40
	v_pk_add_f32 v[40:41], v[32:33], v[64:65]
	v_fmac_f32_e32 v34, v36, v36
	v_fmac_f32_e32 v35, v38, v38
	v_add_f32_e32 v34, v34, v35
	v_mul_f32_e32 v35, v41, v41
	v_fmac_f32_e32 v35, v40, v40
	v_add_f32_e32 v34, v34, v35
	v_mul_f32_e32 v35, v43, v43
	v_fmac_f32_e32 v35, v42, v42
	v_add_f32_e32 v34, v35, v34
	v_add_f32_e32 v46, v46, v34
	v_mov_b32_e32 v47, v46
	s_nop 1
	v_permlane16_swap_b32_e32 v47, v46
	v_lshl_add_u64 v[44:45], v[82:83], 0, v[160:161]
	v_lshl_add_u64 v[76:77], v[84:85], 1, s[24:25]
	v_lshl_add_u64 v[32:33], v[44:45], 2, s[48:49]
	global_store_dwordx4 v[76:77], v[72:75], off
	global_store_dwordx4 v[32:33], v[36:39], off nt
	global_store_dwordx4 v[32:33], v[40:43], off offset:16 nt
	s_waitcnt lgkmcnt(0)
	v_add_f32_e32 v32, v46, v47
	v_mov_b32_e32 v33, v32
	s_nop 1
	v_permlane32_swap_b32_e32 v33, v32
	v_cvt_pk_bf16_f32 v35, v38, v39
	v_lshl_add_u64 v[38:39], v[44:45], 1, s[24:25]
	v_cvt_pk_bf16_f32 v34, v36, v37
	v_cvt_pk_bf16_f32 v36, v40, v41
	v_cvt_pk_bf16_f32 v37, v42, v43
	global_store_dwordx4 v[38:39], v[34:37], off
	s_and_saveexec_b64 s[0:1], vcc
	s_cbranch_execz .LBB0_472
	v_lshl_add_u64 v[34:35], v[96:97], 2, s[10:11]
	s_waitcnt lgkmcnt(0)
	v_add_f32_e32 v32, v32, v33
	global_atomic_add_f32 v[34:35], v32, off
; #define EPI_IT_ROW(it) EPI_ROW((it) >> 2, (it) & 3)
; #define EPI_PACK8(v0, v1) (u32x4){pk2((v0)[0], (v0)[1]), pk2((v0)[2], (v0)[3]), pk2((v1)[0], (v1)[1]), pk2((v1)[2], (v1)[3])}
;     __device__ __forceinline__ void operator()(AccRef acc, const Unit& u, int wr, int wc, int fr, int fq) const {
;     ...
;         for (int bj = 0; bj < 2; ++bj) { const size_t p = (size_t)EPI_IT_ROW(0) * DM + EPI_COL(bj); xc[bj][0] = *(const f32x4*)(xin + p); xc[bj][1] = *(const f32x4*)(xin + p + 4); }
; #pragma unroll
;         for (int it = 0; it < 8; ++it) { const int ai = it >> 2, m = it & 3, row = EPI_IT_ROW(it);
;             if (it + 1 < 8) {
; #pragma unroll
;                 for (int bj = 0; bj < 2; ++bj) { const size_t p = (size_t)EPI_IT_ROW(it + 1) * DM + EPI_COL(bj); xn[bj][0] = *(const f32x4*)(xin + p); xn[bj][1] = *(const f32x4*)(xin + p + 4); } }
;             float q = 0.f;
; #pragma unroll
;             for (int bj = 0; bj < 2; ++bj) { const size_t p = (size_t)row * DM + EPI_COL(bj);
;                 const f32x4 x0 = xc[bj][0] + acc[ai][bj][m][0], x1 = xc[bj][1] + acc[ai][bj][m][1];
;                 __builtin_nontemporal_store(x0, (f32x4*)(xout + p)); __builtin_nontemporal_store(x1, (f32x4*)(xout + p + 4));
;                 *(u32x4*)(xb + p) = EPI_PACK8(x0, x1);
;                 q += EPI_SQ8(x0, x1); }
;             q += __shfl_xor(q, 16); q += __shfl_xor(q, 32);
;             if (fq == 0) atomicAdd(ssout + row, q);
; #pragma unroll
;             for (int bj = 0; bj < 2; ++bj) { xc[bj][0] = xn[bj][0]; xc[bj][1] = xn[bj][1]; } }
.LBB0_472:
	s_or_b64 exec, exec, s[0:1]
	s_waitcnt vmcnt(16)
	v_mov_b64_e32 v[56:57], v[206:207]
	v_mov_b64_e32 v[58:59], v[208:209]
	v_mov_b64_e32 v[60:61], v[210:211]
	v_mov_b64_e32 v[62:63], v[212:213]
	v_mov_b64_e32 v[48:49], v[214:215]
	v_mov_b64_e32 v[50:51], v[216:217]
	v_mov_b64_e32 v[52:53], v[218:219]
	v_mov_b64_e32 v[54:55], v[220:221]
	v_add_u32_e32 v64, 0xb0, v164
	v_ashrrev_i32_e32 v65, 31, v64
	s_waitcnt lgkmcnt(0)
	v_lshlrev_b64 v[32:33], 12, v[64:65]
	v_lshl_add_u64 v[32:33], s[16:17], 0, v[32:33]
	v_lshl_add_u64 v[34:35], v[162:163], 2, v[32:33]
	v_lshl_add_u64 v[36:37], v[160:161], 2, v[32:33]
	s_nop 0
	s_nop 0
	v_lshlrev_b64 v[66:67], 10, v[80:81]
	v_lshl_add_u64 v[68:69], v[66:67], 0, v[162:163]
	v_pk_add_f32 v[30:31], v[30:31], v[62:63]
	v_pk_add_f32 v[28:29], v[28:29], v[60:61]
	v_pk_add_f32 v[24:25], v[24:25], v[56:57]
	v_lshl_add_u64 v[56:57], v[68:69], 2, s[48:49]
	v_pk_add_f32 v[26:27], v[26:27], v[58:59]
	global_store_dwordx4 v[56:57], v[28:31], off nt
	global_store_dwordx4 v[56:57], v[24:27], off offset:16 nt
	v_cvt_pk_bf16_f32 v56, v28, v29
	v_cvt_pk_bf16_f32 v58, v24, v25
	v_pk_add_f32 v[22:23], v[22:23], v[54:55]
	v_mul_f32_e32 v29, v29, v29
	v_fmac_f32_e32 v29, v28, v28
	v_mul_f32_e32 v28, v31, v31
	v_fmac_f32_e32 v28, v30, v30
	v_mul_f32_e32 v25, v25, v25
	v_add_f32_e32 v28, v29, v28
	v_fmac_f32_e32 v25, v24, v24
	v_add_f32_e32 v24, v28, v25
	v_mul_f32_e32 v25, v27, v27
	v_pk_add_f32 v[20:21], v[20:21], v[52:53]
	v_cvt_pk_bf16_f32 v59, v26, v27
	v_fmac_f32_e32 v25, v26, v26
	v_pk_add_f32 v[26:27], v[18:19], v[50:51]
	v_mul_f32_e32 v18, v21, v21
	v_mul_f32_e32 v19, v23, v23
	v_cvt_pk_bf16_f32 v57, v30, v31
	v_add_f32_e32 v30, v25, v24
	v_pk_add_f32 v[24:25], v[16:17], v[48:49]
	v_fmac_f32_e32 v18, v20, v20
	v_fmac_f32_e32 v19, v22, v22
	v_add_f32_e32 v18, v18, v19
	v_mul_f32_e32 v19, v25, v25
	v_fmac_f32_e32 v19, v24, v24
	v_add_f32_e32 v18, v18, v19
	v_mul_f32_e32 v19, v27, v27
	v_fmac_f32_e32 v19, v26, v26
	v_add_f32_e32 v18, v19, v18
	v_add_f32_e32 v30, v30, v18
	v_mov_b32_e32 v31, v30
	s_nop 1
	v_permlane16_swap_b32_e32 v31, v30
	v_lshl_add_u64 v[28:29], v[66:67], 0, v[160:161]
	v_lshl_add_u64 v[60:61], v[68:69], 1, s[24:25]
	v_lshl_add_u64 v[16:17], v[28:29], 2, s[48:49]
	global_store_dwordx4 v[60:61], v[56:59], off
	global_store_dwordx4 v[16:17], v[20:23], off nt
	global_store_dwordx4 v[16:17], v[24:27], off offset:16 nt
	s_waitcnt lgkmcnt(0)
	v_add_f32_e32 v16, v30, v31
	v_mov_b32_e32 v17, v16
	s_nop 1
	v_permlane32_swap_b32_e32 v17, v16
	v_cvt_pk_bf16_f32 v19, v22, v23
	v_lshl_add_u64 v[22:23], v[28:29], 1, s[24:25]
	v_cvt_pk_bf16_f32 v18, v20, v21
	v_cvt_pk_bf16_f32 v20, v24, v25
	v_cvt_pk_bf16_f32 v21, v26, v27
	global_store_dwordx4 v[22:23], v[18:21], off
	s_and_saveexec_b64 s[0:1], vcc
	s_cbranch_execz .LBB0_474
	v_lshl_add_u64 v[18:19], v[80:81], 2, s[10:11]
	s_waitcnt lgkmcnt(0)
	v_add_f32_e32 v16, v16, v17
	global_atomic_add_f32 v[18:19], v16, off
.LBB0_474:
	s_or_b64 exec, exec, s[0:1]
	s_waitcnt vmcnt(12)
	v_mov_b64_e32 v[40:41], v[228:229]
	v_mov_b64_e32 v[42:43], v[230:231]
	v_mov_b64_e32 v[44:45], v[232:233]
	v_mov_b64_e32 v[46:47], v[234:235]
	v_mov_b64_e32 v[32:33], v[236:237]
	v_mov_b64_e32 v[34:35], v[238:239]
	v_mov_b64_e32 v[36:37], v[240:241]
	v_mov_b64_e32 v[38:39], v[242:243]
	v_lshlrev_b64 v[20:21], 10, v[64:65]
	v_lshl_add_u64 v[22:23], v[20:21], 0, v[162:163]
	v_pk_add_f32 v[14:15], v[14:15], v[46:47]
	v_pk_add_f32 v[12:13], v[12:13], v[44:45]
	s_waitcnt lgkmcnt(0)
	v_lshl_add_u64 v[16:17], v[22:23], 2, s[48:49]
	v_pk_add_f32 v[10:11], v[10:11], v[42:43]
	v_pk_add_f32 v[8:9], v[8:9], v[40:41]
	global_store_dwordx4 v[16:17], v[12:15], off nt
	global_store_dwordx4 v[16:17], v[8:11], off offset:16 nt
	v_cvt_pk_bf16_f32 v16, v12, v13
	v_cvt_pk_bf16_f32 v18, v8, v9
	v_pk_add_f32 v[6:7], v[6:7], v[38:39]
	v_mul_f32_e32 v13, v13, v13
	v_fmac_f32_e32 v13, v12, v12
	v_mul_f32_e32 v12, v15, v15
	v_fmac_f32_e32 v12, v14, v14
	v_mul_f32_e32 v9, v9, v9
	v_add_f32_e32 v12, v13, v12
	v_fmac_f32_e32 v9, v8, v8
	v_add_f32_e32 v8, v12, v9
	v_mul_f32_e32 v9, v11, v11
	v_pk_add_f32 v[4:5], v[4:5], v[36:37]
	v_cvt_pk_bf16_f32 v19, v10, v11
	v_fmac_f32_e32 v9, v10, v10
	v_pk_add_f32 v[10:11], v[2:3], v[34:35]
	v_mul_f32_e32 v2, v5, v5
	v_mul_f32_e32 v3, v7, v7
	v_cvt_pk_bf16_f32 v17, v14, v15
	v_add_f32_e32 v14, v9, v8
	v_pk_add_f32 v[8:9], v[0:1], v[32:33]
	v_fmac_f32_e32 v2, v4, v4
	v_fmac_f32_e32 v3, v6, v6
	v_add_f32_e32 v2, v2, v3
	v_mul_f32_e32 v3, v9, v9
	v_fmac_f32_e32 v3, v8, v8
	v_add_f32_e32 v2, v2, v3
	v_mul_f32_e32 v3, v11, v11
	v_fmac_f32_e32 v3, v10, v10
	v_add_f32_e32 v2, v3, v2
	v_add_f32_e32 v14, v14, v2
	v_mov_b32_e32 v15, v14
	s_nop 1
	v_permlane16_swap_b32_e32 v15, v14
	v_lshl_add_u64 v[12:13], v[20:21], 0, v[160:161]
	v_lshl_add_u64 v[22:23], v[22:23], 1, s[24:25]
	v_lshl_add_u64 v[0:1], v[12:13], 2, s[48:49]
	global_store_dwordx4 v[22:23], v[16:19], off
	global_store_dwordx4 v[0:1], v[4:7], off nt
	global_store_dwordx4 v[0:1], v[8:11], off offset:16 nt
	s_waitcnt lgkmcnt(0)
	v_add_f32_e32 v0, v14, v15
	v_mov_b32_e32 v1, v0
	s_nop 1
	v_permlane32_swap_b32_e32 v1, v0
	v_cvt_pk_bf16_f32 v3, v6, v7
	v_lshl_add_u64 v[6:7], v[12:13], 1, s[24:25]
	v_cvt_pk_bf16_f32 v2, v4, v5
	v_cvt_pk_bf16_f32 v4, v8, v9
	v_cvt_pk_bf16_f32 v5, v10, v11
	global_store_dwordx4 v[6:7], v[2:5], off
	s_and_saveexec_b64 s[0:1], vcc
	s_cbranch_execz .LBB0_476
	v_lshl_add_u64 v[2:3], v[64:65], 2, s[10:11]
	s_waitcnt lgkmcnt(0)
	v_add_f32_e32 v0, v0, v1
	global_atomic_add_f32 v[2:3], v0, off

; #define EPI_IT_ROW(it) EPI_ROW((it) >> 2, (it) & 3)
; #define EPI_PACK8(v0, v1) (u32x4){pk2((v0)[0], (v0)[1]), pk2((v0)[2], (v0)[3]), pk2((v1)[0], (v1)[1]), pk2((v1)[2], (v1)[3])}
;     __device__ __forceinline__ void operator()(AccRef acc, const Unit& u, int wr, int wc, int fr, int fq) const {
;     ...
;         f32x4 xc[2][2], xn[2][2];
; #pragma unroll
;         for (int bj = 0; bj < 2; ++bj) { const size_t p = (size_t)EPI_IT_ROW(0) * DM + EPI_COL(bj); xc[bj][0] = *(const f32x4*)(xin + p); xc[bj][1] = *(const f32x4*)(xin + p + 4); }
; #pragma unroll
;         for (int it = 0; it < 8; ++it) { const int ai = it >> 2, m = it & 3, row = EPI_IT_ROW(it);
;             if (it + 1 < 8) {
; #pragma unroll
;                 for (int bj = 0; bj < 2; ++bj) { const size_t p = (size_t)EPI_IT_ROW(it + 1) * DM + EPI_COL(bj); xn[bj][0] = *(const f32x4*)(xin + p); xn[bj][1] = *(const f32x4*)(xin + p + 4); } }
;             float q = 0.f;
; #pragma unroll
;             for (int bj = 0; bj < 2; ++bj) { const size_t p = (size_t)row * DM + EPI_COL(bj);
;                 const f32x4 x0 = xc[bj][0] + acc[ai][bj][m][0], x1 = xc[bj][1] + acc[ai][bj][m][1];
;                 __builtin_nontemporal_store(x0, (f32x4*)(xout + p)); __builtin_nontemporal_store(x1, (f32x4*)(xout + p + 4));
;                 *(u32x4*)(xb + p) = EPI_PACK8(x0, x1);
;                 q += EPI_SQ8(x0, x1); }
;             q += __shfl_xor(q, 16); q += __shfl_xor(q, 32);
;             if (fq == 0) atomicAdd(ssout + row, q);
; #pragma unroll
;             for (int bj = 0; bj < 2; ++bj) { xc[bj][0] = xn[bj][0]; xc[bj][1] = xn[bj][1]; } }
.LBB0_795:
	s_lshl_b32 s0, s74, 8
	v_mov_b32_e32 v128, v180
	v_mov_b32_e32 v186, v177
	s_add_i32 s0, s0, s56
	v_and_b32_e32 v202, 64, v185
	v_add_u32_e32 v164, s0, v128
	s_lshl_b32 s0, s73, 8
	s_or_b32 s0, s0, s57
	v_ashrrev_i32_e32 v165, 31, v164
	v_lshl_add_u32 v162, v186, 3, s0
	v_lshlrev_b64 v[128:129], 12, v[164:165]
	v_ashrrev_i32_e32 v163, 31, v162
	v_add_u32_e32 v160, 0x80, v162
	v_lshl_add_u64 v[128:129], s[48:49], 0, v[128:129]
	v_lshlrev_b64 v[130:131], 2, v[162:163]
	v_ashrrev_i32_e32 v161, 31, v160
	v_lshl_add_u64 v[178:179], v[128:129], 0, v[130:131]
	v_lshlrev_b64 v[132:133], 2, v[160:161]
	global_load_dwordx4 v[170:173], v[178:179], off offset:16
	global_load_dwordx4 v[188:191], v[178:179], off
	v_lshl_add_u64 v[200:201], v[128:129], 0, v[132:133]
	global_load_dwordx4 v[192:195], v[200:201], off
	global_load_dwordx4 v[196:199], v[200:201], off offset:16
	v_add_u32_e32 v166, 16, v164
	v_ashrrev_i32_e32 v167, 31, v166
	v_lshlrev_b64 v[128:129], 12, v[166:167]
	v_lshl_add_u64 v[128:129], s[48:49], 0, v[128:129]
	v_lshl_add_u64 v[174:175], v[128:129], 0, v[130:131]
	v_lshl_add_u64 v[168:169], v[128:129], 0, v[132:133]
	global_load_dwordx4 v[136:139], v[174:175], off offset:16
	global_load_dwordx4 v[140:143], v[174:175], off
	global_load_dwordx4 v[128:131], v[168:169], off offset:16
	global_load_dwordx4 v[132:135], v[168:169], off
	v_add_u32_e32 v244, 32, v164
	v_ashrrev_i32_e32 v245, 31, v244
	v_lshlrev_b64 v[246:247], 12, v[244:245]
	v_lshl_add_u64 v[246:247], s[48:49], 0, v[246:247]
	v_lshl_add_u64 v[248:249], v[162:163], 2, v[246:247]
	v_lshl_add_u64 v[250:251], v[160:161], 2, v[246:247]
	global_load_dwordx4 v[206:209], v[248:249], off offset:16
	global_load_dwordx4 v[210:213], v[248:249], off
	global_load_dwordx4 v[214:217], v[250:251], off offset:16
	global_load_dwordx4 v[218:221], v[250:251], off
	v_add_u32_e32 v244, 48, v164
	v_ashrrev_i32_e32 v245, 31, v244
	v_lshlrev_b64 v[246:247], 12, v[244:245]
	v_lshl_add_u64 v[246:247], s[48:49], 0, v[246:247]
	v_lshl_add_u64 v[248:249], v[162:163], 2, v[246:247]
	v_lshl_add_u64 v[250:251], v[160:161], 2, v[246:247]
	global_load_dwordx4 v[228:231], v[248:249], off offset:16
	global_load_dwordx4 v[232:235], v[248:249], off
	global_load_dwordx4 v[236:239], v[250:251], off offset:16
	global_load_dwordx4 v[240:243], v[250:251], off
	v_xor_b32_e32 v187, 16, v185
	v_add_u32_e32 v202, 64, v202
	v_cmp_lt_i32_e64 s[0:1], v187, v202
	v_cmp_eq_u32_e32 vcc, 0, v186
	v_xor_b32_e32 v203, 32, v185
	v_cndmask_b32_e64 v186, v185, v187, s[0:1]
	v_lshlrev_b32_e32 v186, 2, v186
	v_cmp_lt_i32_e64 s[0:1], v203, v202
	s_waitcnt vmcnt(8)
	v_pk_add_f32 v[122:123], v[122:123], v[172:173]
	v_pk_add_f32 v[126:127], v[126:127], v[190:191]
	v_pk_add_f32 v[124:125], v[124:125], v[188:189]
	v_pk_add_f32 v[118:119], v[118:119], v[194:195]
	v_pk_add_f32 v[116:117], v[116:117], v[192:193]
	v_pk_add_f32 v[120:121], v[120:121], v[170:171]
	v_pk_add_f32 v[170:171], v[112:113], v[196:197]
	global_store_dwordx4 v[178:179], v[124:127], off nt
	global_store_dwordx4 v[178:179], v[120:123], off offset:16 nt
	v_cvt_pk_bf16_f32 v112, v124, v125
	v_cvt_pk_bf16_f32 v113, v126, v127
	v_mul_f32_e32 v178, v117, v117
	v_mul_f32_e32 v125, v125, v125
	v_mul_f32_e32 v127, v127, v127
	v_mul_f32_e32 v179, v119, v119
	v_pk_add_f32 v[172:173], v[114:115], v[198:199]
	v_cvt_pk_bf16_f32 v114, v120, v121
	v_cvt_pk_bf16_f32 v115, v122, v123
	v_mul_f32_e32 v121, v121, v121
	v_mul_f32_e32 v123, v123, v123
	v_mul_f32_e32 v189, v171, v171
	v_fmac_f32_e32 v125, v124, v124
	v_fmac_f32_e32 v127, v126, v126
	v_fmac_f32_e32 v178, v116, v116
	v_fmac_f32_e32 v179, v118, v118
	v_mul_f32_e32 v190, v173, v173
	v_fmac_f32_e32 v121, v120, v120
	v_fmac_f32_e32 v123, v122, v122
	v_fmac_f32_e32 v189, v170, v170
	v_add_f32_e32 v120, v125, v127
	v_add_f32_e32 v122, v178, v179
	v_fmac_f32_e32 v190, v172, v172
	v_add_f32_e32 v120, v120, v121
	v_add_f32_e32 v121, v122, v189
	v_add_f32_e32 v120, v123, v120
	v_add_f32_e32 v121, v190, v121
	v_add_f32_e32 v120, v120, v121
	v_mov_b32_e32 v121, v120
	s_nop 1
	v_permlane16_swap_b32_e32 v121, v120
	v_cndmask_b32_e64 v187, v185, v203, s[0:1]
	v_lshlrev_b64 v[202:203], 10, v[164:165]
	v_lshl_add_u64 v[204:205], v[202:203], 0, v[162:163]
	v_lshl_add_u64 v[204:205], v[204:205], 1, s[30:31]
	global_store_dwordx4 v[204:205], v[112:115], off
	global_store_dwordx4 v[200:201], v[116:119], off nt
	global_store_dwordx4 v[200:201], v[170:173], off offset:16 nt
	s_waitcnt lgkmcnt(0)
	v_add_f32_e32 v112, v120, v121
	v_lshlrev_b32_e32 v187, 2, v187
	v_mov_b32_e32 v113, v112
	s_nop 1
	v_permlane32_swap_b32_e32 v113, v112
	v_lshl_add_u64 v[202:203], v[202:203], 0, v[160:161]
	v_lshl_add_u64 v[114:115], v[202:203], 1, s[30:31]
	v_cvt_pk_bf16_f32 v188, v116, v117
	v_cvt_pk_bf16_f32 v189, v118, v119
	v_cvt_pk_bf16_f32 v190, v170, v171
	v_cvt_pk_bf16_f32 v191, v172, v173
	global_store_dwordx4 v[114:115], v[188:191], off
	s_and_saveexec_b64 s[0:1], vcc
	s_cbranch_execz .LBB0_797
	v_lshl_add_u64 v[114:115], v[164:165], 2, s[12:13]
	s_waitcnt lgkmcnt(0)
	v_add_f32_e32 v112, v112, v113
	global_atomic_add_f32 v[114:115], v112, off
; #define EPI_IT_ROW(it) EPI_ROW((it) >> 2, (it) & 3)
; #define EPI_PACK8(v0, v1) (u32x4){pk2((v0)[0], (v0)[1]), pk2((v0)[2], (v0)[3]), pk2((v1)[0], (v1)[1]), pk2((v1)[2], (v1)[3])}
;     __device__ __forceinline__ void operator()(AccRef acc, const Unit& u, int wr, int wc, int fr, int fq) const {
;     ...
;         for (int bj = 0; bj < 2; ++bj) { const size_t p = (size_t)EPI_IT_ROW(0) * DM + EPI_COL(bj); xc[bj][0] = *(const f32x4*)(xin + p); xc[bj][1] = *(const f32x4*)(xin + p + 4); }
; #pragma unroll
;         for (int it = 0; it < 8; ++it) { const int ai = it >> 2, m = it & 3, row = EPI_IT_ROW(it);
;             if (it + 1 < 8) {
; #pragma unroll
;                 for (int bj = 0; bj < 2; ++bj) { const size_t p = (size_t)EPI_IT_ROW(it + 1) * DM + EPI_COL(bj); xn[bj][0] = *(const f32x4*)(xin + p); xn[bj][1] = *(const f32x4*)(xin + p + 4); } }
;             float q = 0.f;
; #pragma unroll
;             for (int bj = 0; bj < 2; ++bj) { const size_t p = (size_t)row * DM + EPI_COL(bj);
;                 const f32x4 x0 = xc[bj][0] + acc[ai][bj][m][0], x1 = xc[bj][1] + acc[ai][bj][m][1];
;                 __builtin_nontemporal_store(x0, (f32x4*)(xout + p)); __builtin_nontemporal_store(x1, (f32x4*)(xout + p + 4));
;                 *(u32x4*)(xb + p) = EPI_PACK8(x0, x1);
;                 q += EPI_SQ8(x0, x1); }
;             q += __shfl_xor(q, 16); q += __shfl_xor(q, 32);
;             if (fq == 0) atomicAdd(ssout + row, q);
; #pragma unroll
;             for (int bj = 0; bj < 2; ++bj) { xc[bj][0] = xn[bj][0]; xc[bj][1] = xn[bj][1]; } }
.LBB0_797:
	s_or_b64 exec, exec, s[0:1]
	v_add_u32_e32 v170, 32, v164
	v_ashrrev_i32_e32 v171, 31, v170
	s_waitcnt lgkmcnt(0)
	v_lshlrev_b64 v[112:113], 12, v[170:171]
	v_lshl_add_u64 v[112:113], s[48:49], 0, v[112:113]
	v_lshl_add_u64 v[178:179], v[162:163], 2, v[112:113]
	v_lshl_add_u64 v[172:173], v[160:161], 2, v[112:113]
	v_pk_add_f32 v[110:111], v[110:111], v[142:143]
	v_pk_add_f32 v[108:109], v[108:109], v[140:141]
	v_pk_add_f32 v[106:107], v[106:107], v[138:139]
	v_pk_add_f32 v[104:105], v[104:105], v[136:137]
	global_store_dwordx4 v[174:175], v[108:111], off nt
	global_store_dwordx4 v[174:175], v[104:107], off offset:16 nt
	v_cvt_pk_bf16_f32 v136, v108, v109
	v_cvt_pk_bf16_f32 v138, v104, v105
	v_pk_add_f32 v[102:103], v[102:103], v[134:135]
	v_mul_f32_e32 v109, v109, v109
	v_fmac_f32_e32 v109, v108, v108
	v_mul_f32_e32 v108, v111, v111
	v_fmac_f32_e32 v108, v110, v110
	v_mul_f32_e32 v105, v105, v105
	v_add_f32_e32 v108, v109, v108
	v_fmac_f32_e32 v105, v104, v104
	v_add_f32_e32 v104, v108, v105
	v_mul_f32_e32 v105, v107, v107
	v_fmac_f32_e32 v105, v106, v106
	v_pk_add_f32 v[100:101], v[100:101], v[132:133]
	v_cvt_pk_bf16_f32 v137, v110, v111
	v_add_f32_e32 v110, v105, v104
	v_pk_add_f32 v[104:105], v[96:97], v[128:129]
	v_mul_f32_e32 v96, v101, v101
	v_mul_f32_e32 v97, v103, v103
	v_fmac_f32_e32 v96, v100, v100
	v_fmac_f32_e32 v97, v102, v102
	v_add_f32_e32 v96, v96, v97
	v_mul_f32_e32 v97, v105, v105
	v_cvt_pk_bf16_f32 v139, v106, v107
	v_pk_add_f32 v[106:107], v[98:99], v[130:131]
	v_fmac_f32_e32 v97, v104, v104
	v_add_f32_e32 v96, v96, v97
	v_mul_f32_e32 v97, v107, v107
	v_fmac_f32_e32 v97, v106, v106
	v_add_f32_e32 v96, v97, v96
	v_add_f32_e32 v96, v110, v96
	v_mov_b32_e32 v97, v96
	s_nop 1
	v_permlane16_swap_b32_e32 v97, v96
	v_lshlrev_b64 v[188:189], 10, v[166:167]
	v_lshl_add_u64 v[190:191], v[188:189], 0, v[162:163]
	v_lshl_add_u64 v[140:141], v[190:191], 1, s[30:31]
	v_lshl_add_u64 v[108:109], v[188:189], 0, v[160:161]
	s_waitcnt lgkmcnt(0)
	v_add_f32_e32 v96, v96, v97
	v_mov_b32_e32 v97, v96
	s_nop 1
	v_permlane32_swap_b32_e32 v97, v96
	global_store_dwordx4 v[140:141], v[136:139], off
	global_store_dwordx4 v[168:169], v[100:103], off nt
	global_store_dwordx4 v[168:169], v[104:107], off offset:16 nt
	v_cvt_pk_bf16_f32 v99, v102, v103
	v_cvt_pk_bf16_f32 v98, v100, v101
	s_nop 0
	v_lshl_add_u64 v[102:103], v[108:109], 1, s[30:31]
	v_cvt_pk_bf16_f32 v100, v104, v105
	v_cvt_pk_bf16_f32 v101, v106, v107
	global_store_dwordx4 v[102:103], v[98:101], off
	s_and_saveexec_b64 s[0:1], vcc
	s_cbranch_execz .LBB0_799
	v_lshl_add_u64 v[98:99], v[166:167], 2, s[12:13]
	s_waitcnt lgkmcnt(0)
	v_add_f32_e32 v96, v96, v97
	global_atomic_add_f32 v[98:99], v96, off
.LBB0_799:
	s_or_b64 exec, exec, s[0:1]
	s_waitcnt vmcnt(16)
	v_mov_b64_e32 v[120:121], v[206:207]
	v_mov_b64_e32 v[122:123], v[208:209]
	v_mov_b64_e32 v[124:125], v[210:211]
	v_mov_b64_e32 v[126:127], v[212:213]
	v_mov_b64_e32 v[112:113], v[214:215]
	v_mov_b64_e32 v[114:115], v[216:217]
	v_mov_b64_e32 v[116:117], v[218:219]
	v_mov_b64_e32 v[118:119], v[220:221]
	v_add_u32_e32 v244, 128, v164
	v_ashrrev_i32_e32 v245, 31, v244
	v_lshlrev_b64 v[246:247], 12, v[244:245]
	v_lshl_add_u64 v[246:247], s[48:49], 0, v[246:247]
	v_lshl_add_u64 v[248:249], v[162:163], 2, v[246:247]
	v_lshl_add_u64 v[250:251], v[160:161], 2, v[246:247]
	global_load_dwordx4 v[206:209], v[248:249], off offset:16
	global_load_dwordx4 v[210:213], v[248:249], off
	global_load_dwordx4 v[214:217], v[250:251], off offset:16
	global_load_dwordx4 v[218:221], v[250:251], off
	v_add_u32_e32 v128, 48, v164
	v_ashrrev_i32_e32 v129, 31, v128
	s_waitcnt lgkmcnt(0)
	v_lshlrev_b64 v[96:97], 12, v[128:129]
	v_lshl_add_u64 v[96:97], s[48:49], 0, v[96:97]
	v_lshl_add_u64 v[132:133], v[162:163], 2, v[96:97]
	v_lshl_add_u64 v[130:131], v[160:161], 2, v[96:97]
	v_pk_add_f32 v[94:95], v[94:95], v[126:127]
	v_pk_add_f32 v[92:93], v[92:93], v[124:125]
	v_pk_add_f32 v[90:91], v[90:91], v[122:123]
	v_pk_add_f32 v[88:89], v[88:89], v[120:121]
	global_store_dwordx4 v[178:179], v[92:95], off nt
	global_store_dwordx4 v[178:179], v[88:91], off offset:16 nt
	v_cvt_pk_bf16_f32 v120, v92, v93
	v_cvt_pk_bf16_f32 v122, v88, v89
	v_pk_add_f32 v[86:87], v[86:87], v[118:119]
	v_mul_f32_e32 v93, v93, v93
	v_fmac_f32_e32 v93, v92, v92
	v_mul_f32_e32 v92, v95, v95
	v_fmac_f32_e32 v92, v94, v94
	v_mul_f32_e32 v89, v89, v89
	v_add_f32_e32 v92, v93, v92
	v_fmac_f32_e32 v89, v88, v88
	v_add_f32_e32 v88, v92, v89
	v_mul_f32_e32 v89, v91, v91
	v_fmac_f32_e32 v89, v90, v90
	v_pk_add_f32 v[84:85], v[84:85], v[116:117]
	v_cvt_pk_bf16_f32 v121, v94, v95
	v_add_f32_e32 v94, v89, v88
	v_pk_add_f32 v[88:89], v[80:81], v[112:113]
	v_mul_f32_e32 v80, v85, v85
	v_mul_f32_e32 v81, v87, v87
	v_fmac_f32_e32 v80, v84, v84
	v_fmac_f32_e32 v81, v86, v86
	v_add_f32_e32 v80, v80, v81
	v_mul_f32_e32 v81, v89, v89
	v_cvt_pk_bf16_f32 v123, v90, v91
	v_pk_add_f32 v[90:91], v[82:83], v[114:115]
	v_fmac_f32_e32 v81, v88, v88
	v_add_f32_e32 v80, v80, v81
	v_mul_f32_e32 v81, v91, v91
	v_fmac_f32_e32 v81, v90, v90
	v_add_f32_e32 v80, v81, v80
	v_add_f32_e32 v80, v94, v80
	v_mov_b32_e32 v81, v80
	s_nop 1
	v_permlane16_swap_b32_e32 v81, v80
	v_lshlrev_b64 v[134:135], 10, v[170:171]
	v_lshl_add_u64 v[136:137], v[134:135], 0, v[162:163]
	v_lshl_add_u64 v[124:125], v[136:137], 1, s[30:31]
	v_lshl_add_u64 v[92:93], v[134:135], 0, v[160:161]
	s_waitcnt lgkmcnt(0)
	v_add_f32_e32 v80, v80, v81
	v_mov_b32_e32 v81, v80
	s_nop 1
	v_permlane32_swap_b32_e32 v81, v80
	global_store_dwordx4 v[124:125], v[120:123], off
	global_store_dwordx4 v[172:173], v[84:87], off nt
	global_store_dwordx4 v[172:173], v[88:91], off offset:16 nt
	v_cvt_pk_bf16_f32 v83, v86, v87
	v_cvt_pk_bf16_f32 v82, v84, v85
	s_nop 0
	v_lshl_add_u64 v[86:87], v[92:93], 1, s[30:31]
	v_cvt_pk_bf16_f32 v84, v88, v89
	v_cvt_pk_bf16_f32 v85, v90, v91
	global_store_dwordx4 v[86:87], v[82:85], off
	s_and_saveexec_b64 s[0:1], vcc
	s_cbranch_execz .LBB0_801
	v_lshl_add_u64 v[82:83], v[170:171], 2, s[12:13]
	s_waitcnt lgkmcnt(0)
	v_add_f32_e32 v80, v80, v81
	global_atomic_add_f32 v[82:83], v80, off
; #define EPI_IT_ROW(it) EPI_ROW((it) >> 2, (it) & 3)
; #define EPI_PACK8(v0, v1) (u32x4){pk2((v0)[0], (v0)[1]), pk2((v0)[2], (v0)[3]), pk2((v1)[0], (v1)[1]), pk2((v1)[2], (v1)[3])}
;     __device__ __forceinline__ void operator()(AccRef acc, const Unit& u, int wr, int wc, int fr, int fq) const {
;     ...
;         for (int bj = 0; bj < 2; ++bj) { const size_t p = (size_t)EPI_IT_ROW(0) * DM + EPI_COL(bj); xc[bj][0] = *(const f32x4*)(xin + p); xc[bj][1] = *(const f32x4*)(xin + p + 4); }
; #pragma unroll
;         for (int it = 0; it < 8; ++it) { const int ai = it >> 2, m = it & 3, row = EPI_IT_ROW(it);
;             if (it + 1 < 8) {
; #pragma unroll
;                 for (int bj = 0; bj < 2; ++bj) { const size_t p = (size_t)EPI_IT_ROW(it + 1) * DM + EPI_COL(bj); xn[bj][0] = *(const f32x4*)(xin + p); xn[bj][1] = *(const f32x4*)(xin + p + 4); } }
;             float q = 0.f;
; #pragma unroll
;             for (int bj = 0; bj < 2; ++bj) { const size_t p = (size_t)row * DM + EPI_COL(bj);
;                 const f32x4 x0 = xc[bj][0] + acc[ai][bj][m][0], x1 = xc[bj][1] + acc[ai][bj][m][1];
;                 __builtin_nontemporal_store(x0, (f32x4*)(xout + p)); __builtin_nontemporal_store(x1, (f32x4*)(xout + p + 4));
;                 *(u32x4*)(xb + p) = EPI_PACK8(x0, x1);
;                 q += EPI_SQ8(x0, x1); }
;             q += __shfl_xor(q, 16); q += __shfl_xor(q, 32);
;             if (fq == 0) atomicAdd(ssout + row, q);
; #pragma unroll
;             for (int bj = 0; bj < 2; ++bj) { xc[bj][0] = xn[bj][0]; xc[bj][1] = xn[bj][1]; } }
.LBB0_801:
	s_or_b64 exec, exec, s[0:1]
	s_waitcnt vmcnt(22)
	v_mov_b64_e32 v[104:105], v[228:229]
	v_mov_b64_e32 v[106:107], v[230:231]
	v_mov_b64_e32 v[108:109], v[232:233]
	v_mov_b64_e32 v[110:111], v[234:235]
	v_mov_b64_e32 v[96:97], v[236:237]
	v_mov_b64_e32 v[98:99], v[238:239]
	v_mov_b64_e32 v[100:101], v[240:241]
	v_mov_b64_e32 v[102:103], v[242:243]
	v_add_u32_e32 v244, 144, v164
	v_ashrrev_i32_e32 v245, 31, v244
	v_lshlrev_b64 v[246:247], 12, v[244:245]
	v_lshl_add_u64 v[246:247], s[48:49], 0, v[246:247]
	v_lshl_add_u64 v[248:249], v[162:163], 2, v[246:247]
	v_lshl_add_u64 v[250:251], v[160:161], 2, v[246:247]
	global_load_dwordx4 v[228:231], v[248:249], off offset:16
	global_load_dwordx4 v[232:235], v[248:249], off
	global_load_dwordx4 v[236:239], v[250:251], off offset:16
	global_load_dwordx4 v[240:243], v[250:251], off
	v_add_u32_e32 v112, 0x80, v164
	v_ashrrev_i32_e32 v113, 31, v112
	s_waitcnt lgkmcnt(0)
	v_lshlrev_b64 v[80:81], 12, v[112:113]
	v_lshl_add_u64 v[80:81], s[48:49], 0, v[80:81]
	v_lshl_add_u64 v[116:117], v[162:163], 2, v[80:81]
	v_lshl_add_u64 v[114:115], v[160:161], 2, v[80:81]
	v_pk_add_f32 v[78:79], v[78:79], v[110:111]
	v_pk_add_f32 v[76:77], v[76:77], v[108:109]
	v_pk_add_f32 v[74:75], v[74:75], v[106:107]
	v_pk_add_f32 v[72:73], v[72:73], v[104:105]
	global_store_dwordx4 v[132:133], v[76:79], off nt
	global_store_dwordx4 v[132:133], v[72:75], off offset:16 nt
	v_cvt_pk_bf16_f32 v104, v76, v77
	v_cvt_pk_bf16_f32 v106, v72, v73
	v_pk_add_f32 v[70:71], v[70:71], v[102:103]
	v_mul_f32_e32 v77, v77, v77
	v_fmac_f32_e32 v77, v76, v76
	v_mul_f32_e32 v76, v79, v79
	v_fmac_f32_e32 v76, v78, v78
	v_mul_f32_e32 v73, v73, v73
	v_add_f32_e32 v76, v77, v76
	v_fmac_f32_e32 v73, v72, v72
	v_add_f32_e32 v72, v76, v73
	v_mul_f32_e32 v73, v75, v75
	v_fmac_f32_e32 v73, v74, v74
	v_pk_add_f32 v[68:69], v[68:69], v[100:101]
	v_cvt_pk_bf16_f32 v105, v78, v79
	v_add_f32_e32 v78, v73, v72
	v_pk_add_f32 v[72:73], v[64:65], v[96:97]
	v_mul_f32_e32 v64, v69, v69
	v_mul_f32_e32 v65, v71, v71
	v_fmac_f32_e32 v64, v68, v68
	v_fmac_f32_e32 v65, v70, v70
	v_add_f32_e32 v64, v64, v65
	v_mul_f32_e32 v65, v73, v73
	v_cvt_pk_bf16_f32 v107, v74, v75
	v_pk_add_f32 v[74:75], v[66:67], v[98:99]
	v_fmac_f32_e32 v65, v72, v72
	v_add_f32_e32 v64, v64, v65
	v_mul_f32_e32 v65, v75, v75
	v_fmac_f32_e32 v65, v74, v74
	v_add_f32_e32 v64, v65, v64
	v_add_f32_e32 v64, v78, v64
	v_mov_b32_e32 v65, v64
	s_nop 1
	v_permlane16_swap_b32_e32 v65, v64
	v_lshlrev_b64 v[118:119], 10, v[128:129]
	v_lshl_add_u64 v[120:121], v[118:119], 0, v[162:163]
	v_lshl_add_u64 v[108:109], v[120:121], 1, s[30:31]
	v_lshl_add_u64 v[76:77], v[118:119], 0, v[160:161]
	s_waitcnt lgkmcnt(0)
	v_add_f32_e32 v64, v64, v65
	v_mov_b32_e32 v65, v64
	s_nop 1
	v_permlane32_swap_b32_e32 v65, v64
	global_store_dwordx4 v[108:109], v[104:107], off
	global_store_dwordx4 v[130:131], v[68:71], off nt
	global_store_dwordx4 v[130:131], v[72:75], off offset:16 nt
	v_cvt_pk_bf16_f32 v67, v70, v71
	v_cvt_pk_bf16_f32 v66, v68, v69
	s_nop 0
	v_lshl_add_u64 v[70:71], v[76:77], 1, s[30:31]
	v_cvt_pk_bf16_f32 v68, v72, v73
	v_cvt_pk_bf16_f32 v69, v74, v75
	global_store_dwordx4 v[70:71], v[66:69], off
	s_and_saveexec_b64 s[0:1], vcc
	s_cbranch_execz .LBB0_803
	v_lshl_add_u64 v[66:67], v[128:129], 2, s[12:13]
	s_waitcnt lgkmcnt(0)
	v_add_f32_e32 v64, v64, v65
	global_atomic_add_f32 v[66:67], v64, off
.LBB0_803:
	s_or_b64 exec, exec, s[0:1]
	s_waitcnt vmcnt(16)
	v_mov_b64_e32 v[88:89], v[206:207]
	v_mov_b64_e32 v[90:91], v[208:209]
	v_mov_b64_e32 v[92:93], v[210:211]
	v_mov_b64_e32 v[94:95], v[212:213]
	v_mov_b64_e32 v[80:81], v[214:215]
	v_mov_b64_e32 v[82:83], v[216:217]
	v_mov_b64_e32 v[84:85], v[218:219]
	v_mov_b64_e32 v[86:87], v[220:221]
	v_add_u32_e32 v244, 160, v164
	v_ashrrev_i32_e32 v245, 31, v244
	v_lshlrev_b64 v[246:247], 12, v[244:245]
	v_lshl_add_u64 v[246:247], s[48:49], 0, v[246:247]
	v_lshl_add_u64 v[248:249], v[162:163], 2, v[246:247]
	v_lshl_add_u64 v[250:251], v[160:161], 2, v[246:247]
	global_load_dwordx4 v[206:209], v[248:249], off offset:16
	global_load_dwordx4 v[210:213], v[248:249], off
	global_load_dwordx4 v[214:217], v[250:251], off offset:16
	global_load_dwordx4 v[218:221], v[250:251], off
	v_add_u32_e32 v96, 0x90, v164
	v_ashrrev_i32_e32 v97, 31, v96
	s_waitcnt lgkmcnt(0)
	v_lshlrev_b64 v[64:65], 12, v[96:97]
	v_lshl_add_u64 v[64:65], s[48:49], 0, v[64:65]
	v_lshl_add_u64 v[100:101], v[162:163], 2, v[64:65]
	v_lshl_add_u64 v[98:99], v[160:161], 2, v[64:65]
	v_pk_add_f32 v[62:63], v[62:63], v[94:95]
	v_pk_add_f32 v[60:61], v[60:61], v[92:93]
	v_pk_add_f32 v[58:59], v[58:59], v[90:91]
	v_pk_add_f32 v[56:57], v[56:57], v[88:89]
	global_store_dwordx4 v[116:117], v[60:63], off nt
	global_store_dwordx4 v[116:117], v[56:59], off offset:16 nt
	v_cvt_pk_bf16_f32 v88, v60, v61
	v_cvt_pk_bf16_f32 v90, v56, v57
	v_pk_add_f32 v[54:55], v[54:55], v[86:87]
	v_mul_f32_e32 v61, v61, v61
	v_fmac_f32_e32 v61, v60, v60
	v_mul_f32_e32 v60, v63, v63
	v_fmac_f32_e32 v60, v62, v62
	v_mul_f32_e32 v57, v57, v57
	v_add_f32_e32 v60, v61, v60
	v_fmac_f32_e32 v57, v56, v56
	v_add_f32_e32 v56, v60, v57
	v_mul_f32_e32 v57, v59, v59
	v_fmac_f32_e32 v57, v58, v58
	v_pk_add_f32 v[52:53], v[52:53], v[84:85]
	v_cvt_pk_bf16_f32 v89, v62, v63
	v_add_f32_e32 v62, v57, v56
	v_pk_add_f32 v[56:57], v[48:49], v[80:81]
	v_mul_f32_e32 v48, v53, v53
	v_mul_f32_e32 v49, v55, v55
	v_fmac_f32_e32 v48, v52, v52
	v_fmac_f32_e32 v49, v54, v54
	v_add_f32_e32 v48, v48, v49
	v_mul_f32_e32 v49, v57, v57
	v_cvt_pk_bf16_f32 v91, v58, v59
	v_pk_add_f32 v[58:59], v[50:51], v[82:83]
	v_fmac_f32_e32 v49, v56, v56
	v_add_f32_e32 v48, v48, v49
	v_mul_f32_e32 v49, v59, v59
	v_fmac_f32_e32 v49, v58, v58
	v_add_f32_e32 v48, v49, v48
	v_add_f32_e32 v48, v62, v48
	v_mov_b32_e32 v49, v48
	s_nop 1
	v_permlane16_swap_b32_e32 v49, v48
	v_lshlrev_b64 v[102:103], 10, v[112:113]
	v_lshl_add_u64 v[104:105], v[102:103], 0, v[162:163]
	v_lshl_add_u64 v[92:93], v[104:105], 1, s[30:31]
	v_lshl_add_u64 v[60:61], v[102:103], 0, v[160:161]
	s_waitcnt lgkmcnt(0)
	v_add_f32_e32 v48, v48, v49
	v_mov_b32_e32 v49, v48
	s_nop 1
	v_permlane32_swap_b32_e32 v49, v48
	global_store_dwordx4 v[92:93], v[88:91], off
	global_store_dwordx4 v[114:115], v[52:55], off nt
	global_store_dwordx4 v[114:115], v[56:59], off offset:16 nt
	v_cvt_pk_bf16_f32 v51, v54, v55
	v_cvt_pk_bf16_f32 v50, v52, v53
	s_nop 0
	v_lshl_add_u64 v[54:55], v[60:61], 1, s[30:31]
	v_cvt_pk_bf16_f32 v52, v56, v57
	v_cvt_pk_bf16_f32 v53, v58, v59
	global_store_dwordx4 v[54:55], v[50:53], off
	s_and_saveexec_b64 s[0:1], vcc
	s_cbranch_execz .LBB0_805
	v_lshl_add_u64 v[50:51], v[112:113], 2, s[12:13]
	s_waitcnt lgkmcnt(0)
	v_add_f32_e32 v48, v48, v49
	global_atomic_add_f32 v[50:51], v48, off
; #define EPI_IT_ROW(it) EPI_ROW((it) >> 2, (it) & 3)
; #define EPI_PACK8(v0, v1) (u32x4){pk2((v0)[0], (v0)[1]), pk2((v0)[2], (v0)[3]), pk2((v1)[0], (v1)[1]), pk2((v1)[2], (v1)[3])}
;     __device__ __forceinline__ void operator()(AccRef acc, const Unit& u, int wr, int wc, int fr, int fq) const {
;     ...
;         for (int bj = 0; bj < 2; ++bj) { const size_t p = (size_t)EPI_IT_ROW(0) * DM + EPI_COL(bj); xc[bj][0] = *(const f32x4*)(xin + p); xc[bj][1] = *(const f32x4*)(xin + p + 4); }
; #pragma unroll
;         for (int it = 0; it < 8; ++it) { const int ai = it >> 2, m = it & 3, row = EPI_IT_ROW(it);
;             if (it + 1 < 8) {
; #pragma unroll
;                 for (int bj = 0; bj < 2; ++bj) { const size_t p = (size_t)EPI_IT_ROW(it + 1) * DM + EPI_COL(bj); xn[bj][0] = *(const f32x4*)(xin + p); xn[bj][1] = *(const f32x4*)(xin + p + 4); } }
;             float q = 0.f;
; #pragma unroll
;             for (int bj = 0; bj < 2; ++bj) { const size_t p = (size_t)row * DM + EPI_COL(bj);
;                 const f32x4 x0 = xc[bj][0] + acc[ai][bj][m][0], x1 = xc[bj][1] + acc[ai][bj][m][1];
;                 __builtin_nontemporal_store(x0, (f32x4*)(xout + p)); __builtin_nontemporal_store(x1, (f32x4*)(xout + p + 4));
;                 *(u32x4*)(xb + p) = EPI_PACK8(x0, x1);
;                 q += EPI_SQ8(x0, x1); }
;             q += __shfl_xor(q, 16); q += __shfl_xor(q, 32);
;             if (fq == 0) atomicAdd(ssout + row, q);
; #pragma unroll
;             for (int bj = 0; bj < 2; ++bj) { xc[bj][0] = xn[bj][0]; xc[bj][1] = xn[bj][1]; } }
.LBB0_805:
	s_or_b64 exec, exec, s[0:1]
	s_waitcnt vmcnt(16)
	v_mov_b64_e32 v[72:73], v[228:229]
	v_mov_b64_e32 v[74:75], v[230:231]
	v_mov_b64_e32 v[76:77], v[232:233]
	v_mov_b64_e32 v[78:79], v[234:235]
	v_mov_b64_e32 v[64:65], v[236:237]
	v_mov_b64_e32 v[66:67], v[238:239]
	v_mov_b64_e32 v[68:69], v[240:241]
	v_mov_b64_e32 v[70:71], v[242:243]
	v_add_u32_e32 v244, 176, v164
	v_ashrrev_i32_e32 v245, 31, v244
	v_lshlrev_b64 v[246:247], 12, v[244:245]
	v_lshl_add_u64 v[246:247], s[48:49], 0, v[246:247]
	v_lshl_add_u64 v[248:249], v[162:163], 2, v[246:247]
	v_lshl_add_u64 v[250:251], v[160:161], 2, v[246:247]
	global_load_dwordx4 v[228:231], v[248:249], off offset:16
	global_load_dwordx4 v[232:235], v[248:249], off
	global_load_dwordx4 v[236:239], v[250:251], off offset:16
	global_load_dwordx4 v[240:243], v[250:251], off
	v_add_u32_e32 v80, 0xa0, v164
	v_ashrrev_i32_e32 v81, 31, v80
	s_waitcnt lgkmcnt(0)
	v_lshlrev_b64 v[48:49], 12, v[80:81]
	v_lshl_add_u64 v[48:49], s[48:49], 0, v[48:49]
	v_lshl_add_u64 v[84:85], v[162:163], 2, v[48:49]
	v_lshl_add_u64 v[82:83], v[160:161], 2, v[48:49]
	v_pk_add_f32 v[46:47], v[46:47], v[78:79]
	v_pk_add_f32 v[44:45], v[44:45], v[76:77]
	v_pk_add_f32 v[42:43], v[42:43], v[74:75]
	v_pk_add_f32 v[40:41], v[40:41], v[72:73]
	global_store_dwordx4 v[100:101], v[44:47], off nt
	global_store_dwordx4 v[100:101], v[40:43], off offset:16 nt
	v_cvt_pk_bf16_f32 v72, v44, v45
	v_cvt_pk_bf16_f32 v74, v40, v41
	v_pk_add_f32 v[38:39], v[38:39], v[70:71]
	v_mul_f32_e32 v45, v45, v45
	v_fmac_f32_e32 v45, v44, v44
	v_mul_f32_e32 v44, v47, v47
	v_fmac_f32_e32 v44, v46, v46
	v_mul_f32_e32 v41, v41, v41
	v_add_f32_e32 v44, v45, v44
	v_fmac_f32_e32 v41, v40, v40
	v_add_f32_e32 v40, v44, v41
	v_mul_f32_e32 v41, v43, v43
	v_fmac_f32_e32 v41, v42, v42
	v_pk_add_f32 v[36:37], v[36:37], v[68:69]
	v_cvt_pk_bf16_f32 v73, v46, v47
	v_add_f32_e32 v46, v41, v40
	v_pk_add_f32 v[40:41], v[32:33], v[64:65]
	v_mul_f32_e32 v32, v37, v37
	v_mul_f32_e32 v33, v39, v39
	v_fmac_f32_e32 v32, v36, v36
	v_fmac_f32_e32 v33, v38, v38
	v_add_f32_e32 v32, v32, v33
	v_mul_f32_e32 v33, v41, v41
	v_cvt_pk_bf16_f32 v75, v42, v43
	v_pk_add_f32 v[42:43], v[34:35], v[66:67]
	v_fmac_f32_e32 v33, v40, v40
	v_add_f32_e32 v32, v32, v33
	v_mul_f32_e32 v33, v43, v43
	v_fmac_f32_e32 v33, v42, v42
	v_add_f32_e32 v32, v33, v32
	v_add_f32_e32 v32, v46, v32
	v_mov_b32_e32 v33, v32
	s_nop 1
	v_permlane16_swap_b32_e32 v33, v32
	v_lshlrev_b64 v[86:87], 10, v[96:97]
	v_lshl_add_u64 v[88:89], v[86:87], 0, v[162:163]
	v_lshl_add_u64 v[76:77], v[88:89], 1, s[30:31]
	v_lshl_add_u64 v[44:45], v[86:87], 0, v[160:161]
	s_waitcnt lgkmcnt(0)
	v_add_f32_e32 v32, v32, v33
	v_mov_b32_e32 v33, v32
	s_nop 1
	v_permlane32_swap_b32_e32 v33, v32
	global_store_dwordx4 v[76:77], v[72:75], off
	global_store_dwordx4 v[98:99], v[36:39], off nt
	global_store_dwordx4 v[98:99], v[40:43], off offset:16 nt
	v_cvt_pk_bf16_f32 v35, v38, v39
	v_cvt_pk_bf16_f32 v34, v36, v37
	s_nop 0
	v_lshl_add_u64 v[38:39], v[44:45], 1, s[30:31]
	v_cvt_pk_bf16_f32 v36, v40, v41
	v_cvt_pk_bf16_f32 v37, v42, v43
	global_store_dwordx4 v[38:39], v[34:37], off
	s_and_saveexec_b64 s[0:1], vcc
	s_cbranch_execz .LBB0_807
	v_lshl_add_u64 v[34:35], v[96:97], 2, s[12:13]
	s_waitcnt lgkmcnt(0)
	v_add_f32_e32 v32, v32, v33
	global_atomic_add_f32 v[34:35], v32, off
; #define EPI_IT_ROW(it) EPI_ROW((it) >> 2, (it) & 3)
; #define EPI_PACK8(v0, v1) (u32x4){pk2((v0)[0], (v0)[1]), pk2((v0)[2], (v0)[3]), pk2((v1)[0], (v1)[1]), pk2((v1)[2], (v1)[3])}
;     __device__ __forceinline__ void operator()(AccRef acc, const Unit& u, int wr, int wc, int fr, int fq) const {
;     ...
;         for (int bj = 0; bj < 2; ++bj) { const size_t p = (size_t)EPI_IT_ROW(0) * DM + EPI_COL(bj); xc[bj][0] = *(const f32x4*)(xin + p); xc[bj][1] = *(const f32x4*)(xin + p + 4); }
; #pragma unroll
;         for (int it = 0; it < 8; ++it) { const int ai = it >> 2, m = it & 3, row = EPI_IT_ROW(it);
;             if (it + 1 < 8) {
; #pragma unroll
;                 for (int bj = 0; bj < 2; ++bj) { const size_t p = (size_t)EPI_IT_ROW(it + 1) * DM + EPI_COL(bj); xn[bj][0] = *(const f32x4*)(xin + p); xn[bj][1] = *(const f32x4*)(xin + p + 4); } }
;             float q = 0.f;
; #pragma unroll
;             for (int bj = 0; bj < 2; ++bj) { const size_t p = (size_t)row * DM + EPI_COL(bj);
;                 const f32x4 x0 = xc[bj][0] + acc[ai][bj][m][0], x1 = xc[bj][1] + acc[ai][bj][m][1];
;                 __builtin_nontemporal_store(x0, (f32x4*)(xout + p)); __builtin_nontemporal_store(x1, (f32x4*)(xout + p + 4));
;                 *(u32x4*)(xb + p) = EPI_PACK8(x0, x1);
;                 q += EPI_SQ8(x0, x1); }
;             q += __shfl_xor(q, 16); q += __shfl_xor(q, 32);
;             if (fq == 0) atomicAdd(ssout + row, q);
; #pragma unroll
;             for (int bj = 0; bj < 2; ++bj) { xc[bj][0] = xn[bj][0]; xc[bj][1] = xn[bj][1]; } }
.LBB0_807:
	s_or_b64 exec, exec, s[0:1]
	s_waitcnt vmcnt(16)
	v_mov_b64_e32 v[56:57], v[206:207]
	v_mov_b64_e32 v[58:59], v[208:209]
	v_mov_b64_e32 v[60:61], v[210:211]
	v_mov_b64_e32 v[62:63], v[212:213]
	v_mov_b64_e32 v[48:49], v[214:215]
	v_mov_b64_e32 v[50:51], v[216:217]
	v_mov_b64_e32 v[52:53], v[218:219]
	v_mov_b64_e32 v[54:55], v[220:221]
	v_add_u32_e32 v64, 0xb0, v164
	v_ashrrev_i32_e32 v65, 31, v64
	s_waitcnt lgkmcnt(0)
	v_lshlrev_b64 v[32:33], 12, v[64:65]
	v_lshl_add_u64 v[32:33], s[48:49], 0, v[32:33]
	v_lshl_add_u64 v[68:69], v[162:163], 2, v[32:33]
	v_lshl_add_u64 v[66:67], v[160:161], 2, v[32:33]
	v_pk_add_f32 v[30:31], v[30:31], v[62:63]
	v_pk_add_f32 v[28:29], v[28:29], v[60:61]
	v_pk_add_f32 v[26:27], v[26:27], v[58:59]
	v_pk_add_f32 v[24:25], v[24:25], v[56:57]
	global_store_dwordx4 v[84:85], v[28:31], off nt
	global_store_dwordx4 v[84:85], v[24:27], off offset:16 nt
	v_cvt_pk_bf16_f32 v56, v28, v29
	v_cvt_pk_bf16_f32 v58, v24, v25
	v_pk_add_f32 v[22:23], v[22:23], v[54:55]
	v_mul_f32_e32 v29, v29, v29
	v_fmac_f32_e32 v29, v28, v28
	v_mul_f32_e32 v28, v31, v31
	v_fmac_f32_e32 v28, v30, v30
	v_mul_f32_e32 v25, v25, v25
	v_add_f32_e32 v28, v29, v28
	v_fmac_f32_e32 v25, v24, v24
	v_add_f32_e32 v24, v28, v25
	v_mul_f32_e32 v25, v27, v27
	v_fmac_f32_e32 v25, v26, v26
	v_pk_add_f32 v[20:21], v[20:21], v[52:53]
	v_cvt_pk_bf16_f32 v57, v30, v31
	v_add_f32_e32 v30, v25, v24
	v_pk_add_f32 v[24:25], v[16:17], v[48:49]
	v_mul_f32_e32 v16, v21, v21
	v_mul_f32_e32 v17, v23, v23
	v_fmac_f32_e32 v16, v20, v20
	v_fmac_f32_e32 v17, v22, v22
	v_add_f32_e32 v16, v16, v17
	v_mul_f32_e32 v17, v25, v25
	v_cvt_pk_bf16_f32 v59, v26, v27
	v_pk_add_f32 v[26:27], v[18:19], v[50:51]
	v_fmac_f32_e32 v17, v24, v24
	v_add_f32_e32 v16, v16, v17
	v_mul_f32_e32 v17, v27, v27
	v_fmac_f32_e32 v17, v26, v26
	v_add_f32_e32 v16, v17, v16
	v_add_f32_e32 v16, v30, v16
	v_mov_b32_e32 v17, v16
	s_nop 1
	v_permlane16_swap_b32_e32 v17, v16
	v_lshlrev_b64 v[70:71], 10, v[80:81]
	v_lshl_add_u64 v[72:73], v[70:71], 0, v[162:163]
	v_lshl_add_u64 v[60:61], v[72:73], 1, s[30:31]
	v_lshl_add_u64 v[28:29], v[70:71], 0, v[160:161]
	s_waitcnt lgkmcnt(0)
	v_add_f32_e32 v16, v16, v17
	v_mov_b32_e32 v17, v16
	s_nop 1
	v_permlane32_swap_b32_e32 v17, v16
	global_store_dwordx4 v[60:61], v[56:59], off
	global_store_dwordx4 v[82:83], v[20:23], off nt
	global_store_dwordx4 v[82:83], v[24:27], off offset:16 nt
	v_cvt_pk_bf16_f32 v19, v22, v23
	v_cvt_pk_bf16_f32 v18, v20, v21
	s_nop 0
	v_lshl_add_u64 v[22:23], v[28:29], 1, s[30:31]
	v_cvt_pk_bf16_f32 v20, v24, v25
	v_cvt_pk_bf16_f32 v21, v26, v27
	global_store_dwordx4 v[22:23], v[18:21], off
	s_and_saveexec_b64 s[0:1], vcc
	s_cbranch_execz .LBB0_809
	v_lshl_add_u64 v[18:19], v[80:81], 2, s[12:13]
	s_waitcnt lgkmcnt(0)
	v_add_f32_e32 v16, v16, v17
	global_atomic_add_f32 v[18:19], v16, off
.LBB0_809:
	s_or_b64 exec, exec, s[0:1]
	s_waitcnt vmcnt(12)
	v_mov_b64_e32 v[40:41], v[228:229]
	v_mov_b64_e32 v[42:43], v[230:231]
	v_mov_b64_e32 v[44:45], v[232:233]
	v_mov_b64_e32 v[46:47], v[234:235]
	v_mov_b64_e32 v[32:33], v[236:237]
	v_mov_b64_e32 v[34:35], v[238:239]
	v_mov_b64_e32 v[36:37], v[240:241]
	v_mov_b64_e32 v[38:39], v[242:243]
	v_pk_add_f32 v[14:15], v[14:15], v[46:47]
	v_pk_add_f32 v[12:13], v[12:13], v[44:45]
	v_pk_add_f32 v[10:11], v[10:11], v[42:43]
	v_pk_add_f32 v[8:9], v[8:9], v[40:41]
	global_store_dwordx4 v[68:69], v[12:15], off nt
	global_store_dwordx4 v[68:69], v[8:11], off offset:16 nt
	v_cvt_pk_bf16_f32 v16, v12, v13
	v_cvt_pk_bf16_f32 v18, v8, v9
	v_pk_add_f32 v[6:7], v[6:7], v[38:39]
	v_mul_f32_e32 v13, v13, v13
	v_fmac_f32_e32 v13, v12, v12
	v_mul_f32_e32 v12, v15, v15
	v_fmac_f32_e32 v12, v14, v14
	v_mul_f32_e32 v9, v9, v9
	v_add_f32_e32 v12, v13, v12
	v_fmac_f32_e32 v9, v8, v8
	v_add_f32_e32 v8, v12, v9
	v_mul_f32_e32 v9, v11, v11
	v_fmac_f32_e32 v9, v10, v10
	v_pk_add_f32 v[4:5], v[4:5], v[36:37]
	s_waitcnt lgkmcnt(0)
	v_cvt_pk_bf16_f32 v17, v14, v15
	v_add_f32_e32 v14, v9, v8
	v_pk_add_f32 v[8:9], v[0:1], v[32:33]
	v_mul_f32_e32 v0, v5, v5
	v_mul_f32_e32 v1, v7, v7
	v_fmac_f32_e32 v0, v4, v4
	v_fmac_f32_e32 v1, v6, v6
	v_add_f32_e32 v0, v0, v1
	v_mul_f32_e32 v1, v9, v9
	v_cvt_pk_bf16_f32 v19, v10, v11
	v_pk_add_f32 v[10:11], v[2:3], v[34:35]
	v_fmac_f32_e32 v1, v8, v8
	v_add_f32_e32 v0, v0, v1
	v_mul_f32_e32 v1, v11, v11
	v_fmac_f32_e32 v1, v10, v10
	v_add_f32_e32 v0, v1, v0
	v_add_f32_e32 v0, v14, v0
	v_mov_b32_e32 v1, v0
	s_nop 1
	v_permlane16_swap_b32_e32 v1, v0
	v_lshlrev_b64 v[20:21], 10, v[64:65]
	v_lshl_add_u64 v[22:23], v[20:21], 0, v[162:163]
	v_lshl_add_u64 v[22:23], v[22:23], 1, s[30:31]
	v_lshl_add_u64 v[12:13], v[20:21], 0, v[160:161]
	s_waitcnt lgkmcnt(0)
	v_add_f32_e32 v0, v0, v1
	v_mov_b32_e32 v1, v0
	s_nop 1
	v_permlane32_swap_b32_e32 v1, v0
	global_store_dwordx4 v[22:23], v[16:19], off
	global_store_dwordx4 v[66:67], v[4:7], off nt
	global_store_dwordx4 v[66:67], v[8:11], off offset:16 nt
	v_cvt_pk_bf16_f32 v3, v6, v7
	v_cvt_pk_bf16_f32 v2, v4, v5
	s_nop 0
	v_lshl_add_u64 v[6:7], v[12:13], 1, s[30:31]
	v_cvt_pk_bf16_f32 v4, v8, v9
	v_cvt_pk_bf16_f32 v5, v10, v11
	global_store_dwordx4 v[6:7], v[2:5], off
	s_and_saveexec_b64 s[0:1], vcc
	s_cbranch_execz .LBB0_811
	v_lshl_add_u64 v[2:3], v[64:65], 2, s[12:13]
	s_waitcnt lgkmcnt(0)
	v_add_f32_e32 v0, v0, v1
	global_atomic_add_f32 v[2:3], v0, off

; #define EPI_IT_ROW(it) EPI_ROW((it) >> 2, (it) & 3)
; #define EPI_PACK8(v0, v1) (u32x4){pk2((v0)[0], (v0)[1]), pk2((v0)[2], (v0)[3]), pk2((v1)[0], (v1)[1]), pk2((v1)[2], (v1)[3])}
;     __device__ __forceinline__ void operator()(AccRef acc, const Unit& u, int wr, int wc, int fr, int fq) const {
;     ...
;         f32x4 xc[2][2], xn[2][2];
; #pragma unroll
;         for (int bj = 0; bj < 2; ++bj) { const size_t p = (size_t)EPI_IT_ROW(0) * DM + EPI_COL(bj); xc[bj][0] = *(const f32x4*)(xin + p); xc[bj][1] = *(const f32x4*)(xin + p + 4); }
; #pragma unroll
;         for (int it = 0; it < 8; ++it) { const int ai = it >> 2, m = it & 3, row = EPI_IT_ROW(it);
;             if (it + 1 < 8) {
; #pragma unroll
;                 for (int bj = 0; bj < 2; ++bj) { const size_t p = (size_t)EPI_IT_ROW(it + 1) * DM + EPI_COL(bj); xn[bj][0] = *(const f32x4*)(xin + p); xn[bj][1] = *(const f32x4*)(xin + p + 4); } }
;             float q = 0.f;
; #pragma unroll
;             for (int bj = 0; bj < 2; ++bj) { const size_t p = (size_t)row * DM + EPI_COL(bj);
;                 const f32x4 x0 = xc[bj][0] + acc[ai][bj][m][0], x1 = xc[bj][1] + acc[ai][bj][m][1];
;                 __builtin_nontemporal_store(x0, (f32x4*)(xout + p)); __builtin_nontemporal_store(x1, (f32x4*)(xout + p + 4));
;                 *(u32x4*)(xb + p) = EPI_PACK8(x0, x1);
;                 q += EPI_SQ8(x0, x1); }
;             q += __shfl_xor(q, 16); q += __shfl_xor(q, 32);
;             if (fq == 0) atomicAdd(ssout + row, q);
; #pragma unroll
;             for (int bj = 0; bj < 2; ++bj) { xc[bj][0] = xn[bj][0]; xc[bj][1] = xn[bj][1]; } }
.LBB0_1317:
	s_lshl_b32 s1, s34, 8
	v_mov_b32_e32 v128, v180
	v_mov_b32_e32 v186, v177
	s_add_i32 s1, s1, s59
	s_lshl_b32 s0, s0, 8
	s_or_b32 s0, s0, s60
	v_add_u32_e32 v164, s1, v128
	v_ashrrev_i32_e32 v165, 31, v164
	v_lshl_add_u32 v162, v186, 3, s0
	v_lshlrev_b64 v[128:129], 12, v[164:165]
	v_ashrrev_i32_e32 v163, 31, v162
	v_add_u32_e32 v160, 0x80, v162
	v_lshl_add_u64 v[128:129], s[48:49], 0, v[128:129]
	v_lshlrev_b64 v[130:131], 2, v[162:163]
	v_ashrrev_i32_e32 v161, 31, v160
	v_lshl_add_u64 v[178:179], v[128:129], 0, v[130:131]
	v_lshlrev_b64 v[132:133], 2, v[160:161]
	global_load_dwordx4 v[170:173], v[178:179], off offset:16
	global_load_dwordx4 v[188:191], v[178:179], off
	v_lshl_add_u64 v[200:201], v[128:129], 0, v[132:133]
	global_load_dwordx4 v[192:195], v[200:201], off
	global_load_dwordx4 v[196:199], v[200:201], off offset:16
	v_add_u32_e32 v166, 16, v164
	v_ashrrev_i32_e32 v167, 31, v166
	v_lshlrev_b64 v[128:129], 12, v[166:167]
	v_lshl_add_u64 v[128:129], s[48:49], 0, v[128:129]
	v_lshl_add_u64 v[174:175], v[128:129], 0, v[130:131]
	v_lshl_add_u64 v[168:169], v[128:129], 0, v[132:133]
	global_load_dwordx4 v[136:139], v[174:175], off offset:16
	global_load_dwordx4 v[140:143], v[174:175], off
	global_load_dwordx4 v[128:131], v[168:169], off offset:16
	global_load_dwordx4 v[132:135], v[168:169], off
	v_add_u32_e32 v244, 32, v164
	v_ashrrev_i32_e32 v245, 31, v244
	v_lshlrev_b64 v[246:247], 12, v[244:245]
	v_lshl_add_u64 v[246:247], s[48:49], 0, v[246:247]
	v_lshl_add_u64 v[248:249], v[162:163], 2, v[246:247]
	v_lshl_add_u64 v[250:251], v[160:161], 2, v[246:247]
	global_load_dwordx4 v[206:209], v[248:249], off offset:16
	global_load_dwordx4 v[210:213], v[248:249], off
	global_load_dwordx4 v[214:217], v[250:251], off offset:16
	global_load_dwordx4 v[218:221], v[250:251], off
	v_add_u32_e32 v244, 48, v164
	v_ashrrev_i32_e32 v245, 31, v244
	v_lshlrev_b64 v[246:247], 12, v[244:245]
	v_lshl_add_u64 v[246:247], s[48:49], 0, v[246:247]
	v_lshl_add_u64 v[248:249], v[162:163], 2, v[246:247]
	v_lshl_add_u64 v[250:251], v[160:161], 2, v[246:247]
	global_load_dwordx4 v[228:231], v[248:249], off offset:16
	global_load_dwordx4 v[232:235], v[248:249], off
	global_load_dwordx4 v[236:239], v[250:251], off offset:16
	global_load_dwordx4 v[240:243], v[250:251], off
	v_and_b32_e32 v202, 64, v185
	v_xor_b32_e32 v187, 16, v185
	v_add_u32_e32 v202, 64, v202
	v_cmp_lt_i32_e64 s[0:1], v187, v202
	v_cmp_eq_u32_e32 vcc, 0, v186
	v_xor_b32_e32 v203, 32, v185
	v_cndmask_b32_e64 v186, v185, v187, s[0:1]
	v_lshlrev_b32_e32 v186, 2, v186
	v_cmp_lt_i32_e64 s[0:1], v203, v202
	s_waitcnt vmcnt(8)
	v_pk_add_f32 v[122:123], v[122:123], v[172:173]
	v_pk_add_f32 v[126:127], v[126:127], v[190:191]
	v_pk_add_f32 v[124:125], v[124:125], v[188:189]
	v_pk_add_f32 v[118:119], v[118:119], v[194:195]
	v_pk_add_f32 v[116:117], v[116:117], v[192:193]
	v_pk_add_f32 v[120:121], v[120:121], v[170:171]
	v_pk_add_f32 v[170:171], v[112:113], v[196:197]
	global_store_dwordx4 v[178:179], v[124:127], off nt
	global_store_dwordx4 v[178:179], v[120:123], off offset:16 nt
	v_cvt_pk_bf16_f32 v112, v124, v125
	v_cvt_pk_bf16_f32 v113, v126, v127
	v_mul_f32_e32 v178, v117, v117
	v_mul_f32_e32 v125, v125, v125
	v_mul_f32_e32 v127, v127, v127
	v_mul_f32_e32 v179, v119, v119
	v_pk_add_f32 v[172:173], v[114:115], v[198:199]
	v_cvt_pk_bf16_f32 v114, v120, v121
	v_cvt_pk_bf16_f32 v115, v122, v123
	v_mul_f32_e32 v121, v121, v121
	v_mul_f32_e32 v123, v123, v123
	v_mul_f32_e32 v189, v171, v171
	v_fmac_f32_e32 v125, v124, v124
	v_fmac_f32_e32 v127, v126, v126
	v_fmac_f32_e32 v178, v116, v116
	v_fmac_f32_e32 v179, v118, v118
	v_mul_f32_e32 v190, v173, v173
	v_fmac_f32_e32 v121, v120, v120
	v_fmac_f32_e32 v123, v122, v122
	v_fmac_f32_e32 v189, v170, v170
	v_add_f32_e32 v120, v125, v127
	v_add_f32_e32 v122, v178, v179
	v_fmac_f32_e32 v190, v172, v172
	v_add_f32_e32 v120, v120, v121
	v_add_f32_e32 v121, v122, v189
	v_add_f32_e32 v120, v123, v120
	v_add_f32_e32 v121, v190, v121
	v_add_f32_e32 v120, v120, v121
	v_mov_b32_e32 v121, v120
	s_nop 1
	v_permlane16_swap_b32_e32 v121, v120
	v_cndmask_b32_e64 v187, v185, v203, s[0:1]
	v_lshlrev_b64 v[202:203], 10, v[164:165]
	v_lshl_add_u64 v[204:205], v[202:203], 0, v[162:163]
	v_lshl_add_u64 v[204:205], v[204:205], 1, s[24:25]
	global_store_dwordx4 v[204:205], v[112:115], off
	global_store_dwordx4 v[200:201], v[116:119], off nt
	global_store_dwordx4 v[200:201], v[170:173], off offset:16 nt
	s_waitcnt lgkmcnt(0)
	v_add_f32_e32 v112, v120, v121
	v_lshlrev_b32_e32 v187, 2, v187
	v_mov_b32_e32 v113, v112
	s_nop 1
	v_permlane32_swap_b32_e32 v113, v112
	v_lshl_add_u64 v[202:203], v[202:203], 0, v[160:161]
	v_lshl_add_u64 v[114:115], v[202:203], 1, s[24:25]
	v_cvt_pk_bf16_f32 v188, v116, v117
	v_cvt_pk_bf16_f32 v189, v118, v119
	v_cvt_pk_bf16_f32 v190, v170, v171
	v_cvt_pk_bf16_f32 v191, v172, v173
	global_store_dwordx4 v[114:115], v[188:191], off
	s_and_saveexec_b64 s[0:1], vcc
	v_readlane_b32 s72, v254, 6
	v_readlane_b32 s73, v254, 7
	v_readlane_b32 s74, v254, 8
	v_readlane_b32 s75, v254, 9
	s_cbranch_execz .LBB0_1319
	v_lshl_add_u64 v[114:115], v[164:165], 2, s[10:11]
	s_waitcnt lgkmcnt(0)
	v_add_f32_e32 v112, v112, v113
	global_atomic_add_f32 v[114:115], v112, off
; #define EPI_IT_ROW(it) EPI_ROW((it) >> 2, (it) & 3)
; #define EPI_PACK8(v0, v1) (u32x4){pk2((v0)[0], (v0)[1]), pk2((v0)[2], (v0)[3]), pk2((v1)[0], (v1)[1]), pk2((v1)[2], (v1)[3])}
;     __device__ __forceinline__ void operator()(AccRef acc, const Unit& u, int wr, int wc, int fr, int fq) const {
;     ...
;         for (int bj = 0; bj < 2; ++bj) { const size_t p = (size_t)EPI_IT_ROW(0) * DM + EPI_COL(bj); xc[bj][0] = *(const f32x4*)(xin + p); xc[bj][1] = *(const f32x4*)(xin + p + 4); }
; #pragma unroll
;         for (int it = 0; it < 8; ++it) { const int ai = it >> 2, m = it & 3, row = EPI_IT_ROW(it);
;             if (it + 1 < 8) {
; #pragma unroll
;                 for (int bj = 0; bj < 2; ++bj) { const size_t p = (size_t)EPI_IT_ROW(it + 1) * DM + EPI_COL(bj); xn[bj][0] = *(const f32x4*)(xin + p); xn[bj][1] = *(const f32x4*)(xin + p + 4); } }
;             float q = 0.f;
; #pragma unroll
;             for (int bj = 0; bj < 2; ++bj) { const size_t p = (size_t)row * DM + EPI_COL(bj);
;                 const f32x4 x0 = xc[bj][0] + acc[ai][bj][m][0], x1 = xc[bj][1] + acc[ai][bj][m][1];
;                 __builtin_nontemporal_store(x0, (f32x4*)(xout + p)); __builtin_nontemporal_store(x1, (f32x4*)(xout + p + 4));
;                 *(u32x4*)(xb + p) = EPI_PACK8(x0, x1);
;                 q += EPI_SQ8(x0, x1); }
;             q += __shfl_xor(q, 16); q += __shfl_xor(q, 32);
;             if (fq == 0) atomicAdd(ssout + row, q);
; #pragma unroll
;             for (int bj = 0; bj < 2; ++bj) { xc[bj][0] = xn[bj][0]; xc[bj][1] = xn[bj][1]; } }
.LBB0_1319:
	s_or_b64 exec, exec, s[0:1]
	v_add_u32_e32 v170, 32, v164
	v_ashrrev_i32_e32 v171, 31, v170
	s_waitcnt lgkmcnt(0)
	v_lshlrev_b64 v[112:113], 12, v[170:171]
	v_lshl_add_u64 v[112:113], s[48:49], 0, v[112:113]
	v_lshl_add_u64 v[178:179], v[162:163], 2, v[112:113]
	v_lshl_add_u64 v[172:173], v[160:161], 2, v[112:113]
	v_pk_add_f32 v[110:111], v[110:111], v[142:143]
	v_pk_add_f32 v[108:109], v[108:109], v[140:141]
	v_pk_add_f32 v[106:107], v[106:107], v[138:139]
	v_pk_add_f32 v[104:105], v[104:105], v[136:137]
	global_store_dwordx4 v[174:175], v[108:111], off nt
	global_store_dwordx4 v[174:175], v[104:107], off offset:16 nt
	v_cvt_pk_bf16_f32 v136, v108, v109
	v_cvt_pk_bf16_f32 v138, v104, v105
	v_pk_add_f32 v[102:103], v[102:103], v[134:135]
	v_mul_f32_e32 v109, v109, v109
	v_fmac_f32_e32 v109, v108, v108
	v_mul_f32_e32 v108, v111, v111
	v_fmac_f32_e32 v108, v110, v110
	v_mul_f32_e32 v105, v105, v105
	v_add_f32_e32 v108, v109, v108
	v_fmac_f32_e32 v105, v104, v104
	v_add_f32_e32 v104, v108, v105
	v_mul_f32_e32 v105, v107, v107
	v_fmac_f32_e32 v105, v106, v106
	v_pk_add_f32 v[100:101], v[100:101], v[132:133]
	v_cvt_pk_bf16_f32 v137, v110, v111
	v_add_f32_e32 v110, v105, v104
	v_pk_add_f32 v[104:105], v[96:97], v[128:129]
	v_mul_f32_e32 v96, v101, v101
	v_mul_f32_e32 v97, v103, v103
	v_fmac_f32_e32 v96, v100, v100
	v_fmac_f32_e32 v97, v102, v102
	v_add_f32_e32 v96, v96, v97
	v_mul_f32_e32 v97, v105, v105
	v_cvt_pk_bf16_f32 v139, v106, v107
	v_pk_add_f32 v[106:107], v[98:99], v[130:131]
	v_fmac_f32_e32 v97, v104, v104
	v_add_f32_e32 v96, v96, v97
	v_mul_f32_e32 v97, v107, v107
	v_fmac_f32_e32 v97, v106, v106
	v_add_f32_e32 v96, v97, v96
	v_add_f32_e32 v96, v110, v96
	v_mov_b32_e32 v97, v96
	s_nop 1
	v_permlane16_swap_b32_e32 v97, v96
	v_lshlrev_b64 v[188:189], 10, v[166:167]
	v_lshl_add_u64 v[190:191], v[188:189], 0, v[162:163]
	v_lshl_add_u64 v[140:141], v[190:191], 1, s[24:25]
	v_lshl_add_u64 v[108:109], v[188:189], 0, v[160:161]
	s_waitcnt lgkmcnt(0)
	v_add_f32_e32 v96, v96, v97
	v_mov_b32_e32 v97, v96
	s_nop 1
	v_permlane32_swap_b32_e32 v97, v96
	global_store_dwordx4 v[140:141], v[136:139], off
	global_store_dwordx4 v[168:169], v[100:103], off nt
	global_store_dwordx4 v[168:169], v[104:107], off offset:16 nt
	v_cvt_pk_bf16_f32 v99, v102, v103
	v_cvt_pk_bf16_f32 v98, v100, v101
	s_nop 0
	v_lshl_add_u64 v[102:103], v[108:109], 1, s[24:25]
	v_cvt_pk_bf16_f32 v100, v104, v105
	v_cvt_pk_bf16_f32 v101, v106, v107
	global_store_dwordx4 v[102:103], v[98:101], off
	s_and_saveexec_b64 s[0:1], vcc
	s_cbranch_execz .LBB0_1321
	v_lshl_add_u64 v[98:99], v[166:167], 2, s[10:11]
	s_waitcnt lgkmcnt(0)
	v_add_f32_e32 v96, v96, v97
	global_atomic_add_f32 v[98:99], v96, off
.LBB0_1321:
	s_or_b64 exec, exec, s[0:1]
	s_waitcnt vmcnt(16)
	v_mov_b64_e32 v[120:121], v[206:207]
	v_mov_b64_e32 v[122:123], v[208:209]
	v_mov_b64_e32 v[124:125], v[210:211]
	v_mov_b64_e32 v[126:127], v[212:213]
	v_mov_b64_e32 v[112:113], v[214:215]
	v_mov_b64_e32 v[114:115], v[216:217]
	v_mov_b64_e32 v[116:117], v[218:219]
	v_mov_b64_e32 v[118:119], v[220:221]
	v_add_u32_e32 v244, 128, v164
	v_ashrrev_i32_e32 v245, 31, v244
	v_lshlrev_b64 v[246:247], 12, v[244:245]
	v_lshl_add_u64 v[246:247], s[48:49], 0, v[246:247]
	v_lshl_add_u64 v[248:249], v[162:163], 2, v[246:247]
	v_lshl_add_u64 v[250:251], v[160:161], 2, v[246:247]
	global_load_dwordx4 v[206:209], v[248:249], off offset:16
	global_load_dwordx4 v[210:213], v[248:249], off
	global_load_dwordx4 v[214:217], v[250:251], off offset:16
	global_load_dwordx4 v[218:221], v[250:251], off
	v_add_u32_e32 v128, 48, v164
	v_ashrrev_i32_e32 v129, 31, v128
	s_waitcnt lgkmcnt(0)
	v_lshlrev_b64 v[96:97], 12, v[128:129]
	v_lshl_add_u64 v[96:97], s[48:49], 0, v[96:97]
	v_lshl_add_u64 v[132:133], v[162:163], 2, v[96:97]
	v_lshl_add_u64 v[130:131], v[160:161], 2, v[96:97]
	v_pk_add_f32 v[94:95], v[94:95], v[126:127]
	v_pk_add_f32 v[92:93], v[92:93], v[124:125]
	v_pk_add_f32 v[90:91], v[90:91], v[122:123]
	v_pk_add_f32 v[88:89], v[88:89], v[120:121]
	global_store_dwordx4 v[178:179], v[92:95], off nt
	global_store_dwordx4 v[178:179], v[88:91], off offset:16 nt
	v_cvt_pk_bf16_f32 v120, v92, v93
	v_cvt_pk_bf16_f32 v122, v88, v89
	v_pk_add_f32 v[86:87], v[86:87], v[118:119]
	v_mul_f32_e32 v93, v93, v93
	v_fmac_f32_e32 v93, v92, v92
	v_mul_f32_e32 v92, v95, v95
	v_fmac_f32_e32 v92, v94, v94
	v_mul_f32_e32 v89, v89, v89
	v_add_f32_e32 v92, v93, v92
	v_fmac_f32_e32 v89, v88, v88
	v_add_f32_e32 v88, v92, v89
	v_mul_f32_e32 v89, v91, v91
	v_fmac_f32_e32 v89, v90, v90
	v_pk_add_f32 v[84:85], v[84:85], v[116:117]
	v_cvt_pk_bf16_f32 v121, v94, v95
	v_add_f32_e32 v94, v89, v88
	v_pk_add_f32 v[88:89], v[80:81], v[112:113]
	v_mul_f32_e32 v80, v85, v85
	v_mul_f32_e32 v81, v87, v87
	v_fmac_f32_e32 v80, v84, v84
	v_fmac_f32_e32 v81, v86, v86
	v_add_f32_e32 v80, v80, v81
	v_mul_f32_e32 v81, v89, v89
	v_cvt_pk_bf16_f32 v123, v90, v91
	v_pk_add_f32 v[90:91], v[82:83], v[114:115]
	v_fmac_f32_e32 v81, v88, v88
	v_add_f32_e32 v80, v80, v81
	v_mul_f32_e32 v81, v91, v91
	v_fmac_f32_e32 v81, v90, v90
	v_add_f32_e32 v80, v81, v80
	v_add_f32_e32 v80, v94, v80
	v_mov_b32_e32 v81, v80
	s_nop 1
	v_permlane16_swap_b32_e32 v81, v80
	v_lshlrev_b64 v[134:135], 10, v[170:171]
	v_lshl_add_u64 v[136:137], v[134:135], 0, v[162:163]
	v_lshl_add_u64 v[124:125], v[136:137], 1, s[24:25]
	v_lshl_add_u64 v[92:93], v[134:135], 0, v[160:161]
	s_waitcnt lgkmcnt(0)
	v_add_f32_e32 v80, v80, v81
	v_mov_b32_e32 v81, v80
	s_nop 1
	v_permlane32_swap_b32_e32 v81, v80
	global_store_dwordx4 v[124:125], v[120:123], off
	global_store_dwordx4 v[172:173], v[84:87], off nt
	global_store_dwordx4 v[172:173], v[88:91], off offset:16 nt
	v_cvt_pk_bf16_f32 v83, v86, v87
	v_cvt_pk_bf16_f32 v82, v84, v85
	s_nop 0
	v_lshl_add_u64 v[86:87], v[92:93], 1, s[24:25]
	v_cvt_pk_bf16_f32 v84, v88, v89
	v_cvt_pk_bf16_f32 v85, v90, v91
	global_store_dwordx4 v[86:87], v[82:85], off
	s_and_saveexec_b64 s[0:1], vcc
	s_cbranch_execz .LBB0_1323
	v_lshl_add_u64 v[82:83], v[170:171], 2, s[10:11]
	s_waitcnt lgkmcnt(0)
	v_add_f32_e32 v80, v80, v81
	global_atomic_add_f32 v[82:83], v80, off
; #define EPI_IT_ROW(it) EPI_ROW((it) >> 2, (it) & 3)
; #define EPI_PACK8(v0, v1) (u32x4){pk2((v0)[0], (v0)[1]), pk2((v0)[2], (v0)[3]), pk2((v1)[0], (v1)[1]), pk2((v1)[2], (v1)[3])}
;     __device__ __forceinline__ void operator()(AccRef acc, const Unit& u, int wr, int wc, int fr, int fq) const {
;     ...
;         for (int bj = 0; bj < 2; ++bj) { const size_t p = (size_t)EPI_IT_ROW(0) * DM + EPI_COL(bj); xc[bj][0] = *(const f32x4*)(xin + p); xc[bj][1] = *(const f32x4*)(xin + p + 4); }
; #pragma unroll
;         for (int it = 0; it < 8; ++it) { const int ai = it >> 2, m = it & 3, row = EPI_IT_ROW(it);
;             if (it + 1 < 8) {
; #pragma unroll
;                 for (int bj = 0; bj < 2; ++bj) { const size_t p = (size_t)EPI_IT_ROW(it + 1) * DM + EPI_COL(bj); xn[bj][0] = *(const f32x4*)(xin + p); xn[bj][1] = *(const f32x4*)(xin + p + 4); } }
;             float q = 0.f;
; #pragma unroll
;             for (int bj = 0; bj < 2; ++bj) { const size_t p = (size_t)row * DM + EPI_COL(bj);
;                 const f32x4 x0 = xc[bj][0] + acc[ai][bj][m][0], x1 = xc[bj][1] + acc[ai][bj][m][1];
;                 __builtin_nontemporal_store(x0, (f32x4*)(xout + p)); __builtin_nontemporal_store(x1, (f32x4*)(xout + p + 4));
;                 *(u32x4*)(xb + p) = EPI_PACK8(x0, x1);
;                 q += EPI_SQ8(x0, x1); }
;             q += __shfl_xor(q, 16); q += __shfl_xor(q, 32);
;             if (fq == 0) atomicAdd(ssout + row, q);
; #pragma unroll
;             for (int bj = 0; bj < 2; ++bj) { xc[bj][0] = xn[bj][0]; xc[bj][1] = xn[bj][1]; } }
.LBB0_1323:
	s_or_b64 exec, exec, s[0:1]
	s_waitcnt vmcnt(22)
	v_mov_b64_e32 v[104:105], v[228:229]
	v_mov_b64_e32 v[106:107], v[230:231]
	v_mov_b64_e32 v[108:109], v[232:233]
	v_mov_b64_e32 v[110:111], v[234:235]
	v_mov_b64_e32 v[96:97], v[236:237]
	v_mov_b64_e32 v[98:99], v[238:239]
	v_mov_b64_e32 v[100:101], v[240:241]
	v_mov_b64_e32 v[102:103], v[242:243]
	v_add_u32_e32 v244, 144, v164
	v_ashrrev_i32_e32 v245, 31, v244
	v_lshlrev_b64 v[246:247], 12, v[244:245]
	v_lshl_add_u64 v[246:247], s[48:49], 0, v[246:247]
	v_lshl_add_u64 v[248:249], v[162:163], 2, v[246:247]
	v_lshl_add_u64 v[250:251], v[160:161], 2, v[246:247]
	global_load_dwordx4 v[228:231], v[248:249], off offset:16
	global_load_dwordx4 v[232:235], v[248:249], off
	global_load_dwordx4 v[236:239], v[250:251], off offset:16
	global_load_dwordx4 v[240:243], v[250:251], off
	v_add_u32_e32 v112, 0x80, v164
	v_ashrrev_i32_e32 v113, 31, v112
	s_waitcnt lgkmcnt(0)
	v_lshlrev_b64 v[80:81], 12, v[112:113]
	v_lshl_add_u64 v[80:81], s[48:49], 0, v[80:81]
	v_lshl_add_u64 v[116:117], v[162:163], 2, v[80:81]
	v_lshl_add_u64 v[114:115], v[160:161], 2, v[80:81]
	v_pk_add_f32 v[78:79], v[78:79], v[110:111]
	v_pk_add_f32 v[76:77], v[76:77], v[108:109]
	v_pk_add_f32 v[74:75], v[74:75], v[106:107]
	v_pk_add_f32 v[72:73], v[72:73], v[104:105]
	global_store_dwordx4 v[132:133], v[76:79], off nt
	global_store_dwordx4 v[132:133], v[72:75], off offset:16 nt
	v_cvt_pk_bf16_f32 v104, v76, v77
	v_cvt_pk_bf16_f32 v106, v72, v73
	v_pk_add_f32 v[70:71], v[70:71], v[102:103]
	v_mul_f32_e32 v77, v77, v77
	v_fmac_f32_e32 v77, v76, v76
	v_mul_f32_e32 v76, v79, v79
	v_fmac_f32_e32 v76, v78, v78
	v_mul_f32_e32 v73, v73, v73
	v_add_f32_e32 v76, v77, v76
	v_fmac_f32_e32 v73, v72, v72
	v_add_f32_e32 v72, v76, v73
	v_mul_f32_e32 v73, v75, v75
	v_fmac_f32_e32 v73, v74, v74
	v_pk_add_f32 v[68:69], v[68:69], v[100:101]
	v_cvt_pk_bf16_f32 v105, v78, v79
	v_add_f32_e32 v78, v73, v72
	v_pk_add_f32 v[72:73], v[64:65], v[96:97]
	v_mul_f32_e32 v64, v69, v69
	v_mul_f32_e32 v65, v71, v71
	v_fmac_f32_e32 v64, v68, v68
	v_fmac_f32_e32 v65, v70, v70
	v_add_f32_e32 v64, v64, v65
	v_mul_f32_e32 v65, v73, v73
	v_cvt_pk_bf16_f32 v107, v74, v75
	v_pk_add_f32 v[74:75], v[66:67], v[98:99]
	v_fmac_f32_e32 v65, v72, v72
	v_add_f32_e32 v64, v64, v65
	v_mul_f32_e32 v65, v75, v75
	v_fmac_f32_e32 v65, v74, v74
	v_add_f32_e32 v64, v65, v64
	v_add_f32_e32 v64, v78, v64
	v_mov_b32_e32 v65, v64
	s_nop 1
	v_permlane16_swap_b32_e32 v65, v64
	v_lshlrev_b64 v[118:119], 10, v[128:129]
	v_lshl_add_u64 v[120:121], v[118:119], 0, v[162:163]
	v_lshl_add_u64 v[108:109], v[120:121], 1, s[24:25]
	v_lshl_add_u64 v[76:77], v[118:119], 0, v[160:161]
	s_waitcnt lgkmcnt(0)
	v_add_f32_e32 v64, v64, v65
	v_mov_b32_e32 v65, v64
	s_nop 1
	v_permlane32_swap_b32_e32 v65, v64
	global_store_dwordx4 v[108:109], v[104:107], off
	global_store_dwordx4 v[130:131], v[68:71], off nt
	global_store_dwordx4 v[130:131], v[72:75], off offset:16 nt
	v_cvt_pk_bf16_f32 v67, v70, v71
	v_cvt_pk_bf16_f32 v66, v68, v69
	s_nop 0
	v_lshl_add_u64 v[70:71], v[76:77], 1, s[24:25]
	v_cvt_pk_bf16_f32 v68, v72, v73
	v_cvt_pk_bf16_f32 v69, v74, v75
	global_store_dwordx4 v[70:71], v[66:69], off
	s_and_saveexec_b64 s[0:1], vcc
	s_cbranch_execz .LBB0_1325
	v_lshl_add_u64 v[66:67], v[128:129], 2, s[10:11]
	s_waitcnt lgkmcnt(0)
	v_add_f32_e32 v64, v64, v65
	global_atomic_add_f32 v[66:67], v64, off
.LBB0_1325:
	s_or_b64 exec, exec, s[0:1]
	s_waitcnt vmcnt(16)
	v_mov_b64_e32 v[88:89], v[206:207]
	v_mov_b64_e32 v[90:91], v[208:209]
	v_mov_b64_e32 v[92:93], v[210:211]
	v_mov_b64_e32 v[94:95], v[212:213]
	v_mov_b64_e32 v[80:81], v[214:215]
	v_mov_b64_e32 v[82:83], v[216:217]
	v_mov_b64_e32 v[84:85], v[218:219]
	v_mov_b64_e32 v[86:87], v[220:221]
	v_add_u32_e32 v244, 160, v164
	v_ashrrev_i32_e32 v245, 31, v244
	v_lshlrev_b64 v[246:247], 12, v[244:245]
	v_lshl_add_u64 v[246:247], s[48:49], 0, v[246:247]
	v_lshl_add_u64 v[248:249], v[162:163], 2, v[246:247]
	v_lshl_add_u64 v[250:251], v[160:161], 2, v[246:247]
	global_load_dwordx4 v[206:209], v[248:249], off offset:16
	global_load_dwordx4 v[210:213], v[248:249], off
	global_load_dwordx4 v[214:217], v[250:251], off offset:16
	global_load_dwordx4 v[218:221], v[250:251], off
	v_add_u32_e32 v96, 0x90, v164
	v_ashrrev_i32_e32 v97, 31, v96
	s_waitcnt lgkmcnt(0)
	v_lshlrev_b64 v[64:65], 12, v[96:97]
	v_lshl_add_u64 v[64:65], s[48:49], 0, v[64:65]
	v_lshl_add_u64 v[100:101], v[162:163], 2, v[64:65]
	v_lshl_add_u64 v[98:99], v[160:161], 2, v[64:65]
	v_pk_add_f32 v[62:63], v[62:63], v[94:95]
	v_pk_add_f32 v[60:61], v[60:61], v[92:93]
	v_pk_add_f32 v[58:59], v[58:59], v[90:91]
	v_pk_add_f32 v[56:57], v[56:57], v[88:89]
	global_store_dwordx4 v[116:117], v[60:63], off nt
	global_store_dwordx4 v[116:117], v[56:59], off offset:16 nt
	v_cvt_pk_bf16_f32 v88, v60, v61
	v_cvt_pk_bf16_f32 v90, v56, v57
	v_pk_add_f32 v[54:55], v[54:55], v[86:87]
	v_mul_f32_e32 v61, v61, v61
	v_fmac_f32_e32 v61, v60, v60
	v_mul_f32_e32 v60, v63, v63
	v_fmac_f32_e32 v60, v62, v62
	v_mul_f32_e32 v57, v57, v57
	v_add_f32_e32 v60, v61, v60
	v_fmac_f32_e32 v57, v56, v56
	v_add_f32_e32 v56, v60, v57
	v_mul_f32_e32 v57, v59, v59
	v_fmac_f32_e32 v57, v58, v58
	v_pk_add_f32 v[52:53], v[52:53], v[84:85]
	v_cvt_pk_bf16_f32 v89, v62, v63
	v_add_f32_e32 v62, v57, v56
	v_pk_add_f32 v[56:57], v[48:49], v[80:81]
	v_mul_f32_e32 v48, v53, v53
	v_mul_f32_e32 v49, v55, v55
	v_fmac_f32_e32 v48, v52, v52
	v_fmac_f32_e32 v49, v54, v54
	v_add_f32_e32 v48, v48, v49
	v_mul_f32_e32 v49, v57, v57
	v_cvt_pk_bf16_f32 v91, v58, v59
	v_pk_add_f32 v[58:59], v[50:51], v[82:83]
	v_fmac_f32_e32 v49, v56, v56
	v_add_f32_e32 v48, v48, v49
	v_mul_f32_e32 v49, v59, v59
	v_fmac_f32_e32 v49, v58, v58
	v_add_f32_e32 v48, v49, v48
	v_add_f32_e32 v48, v62, v48
	v_mov_b32_e32 v49, v48
	s_nop 1
	v_permlane16_swap_b32_e32 v49, v48
	v_lshlrev_b64 v[102:103], 10, v[112:113]
	v_lshl_add_u64 v[104:105], v[102:103], 0, v[162:163]
	v_lshl_add_u64 v[92:93], v[104:105], 1, s[24:25]
	v_lshl_add_u64 v[60:61], v[102:103], 0, v[160:161]
	s_waitcnt lgkmcnt(0)
	v_add_f32_e32 v48, v48, v49
	v_mov_b32_e32 v49, v48
	s_nop 1
	v_permlane32_swap_b32_e32 v49, v48
	global_store_dwordx4 v[92:93], v[88:91], off
	global_store_dwordx4 v[114:115], v[52:55], off nt
	global_store_dwordx4 v[114:115], v[56:59], off offset:16 nt
	v_cvt_pk_bf16_f32 v51, v54, v55
	v_cvt_pk_bf16_f32 v50, v52, v53
	s_nop 0
	v_lshl_add_u64 v[54:55], v[60:61], 1, s[24:25]
	v_cvt_pk_bf16_f32 v52, v56, v57
	v_cvt_pk_bf16_f32 v53, v58, v59
	global_store_dwordx4 v[54:55], v[50:53], off
	s_and_saveexec_b64 s[0:1], vcc
	s_cbranch_execz .LBB0_1327
	v_lshl_add_u64 v[50:51], v[112:113], 2, s[10:11]
	s_waitcnt lgkmcnt(0)
	v_add_f32_e32 v48, v48, v49
	global_atomic_add_f32 v[50:51], v48, off
; #define EPI_IT_ROW(it) EPI_ROW((it) >> 2, (it) & 3)
; #define EPI_PACK8(v0, v1) (u32x4){pk2((v0)[0], (v0)[1]), pk2((v0)[2], (v0)[3]), pk2((v1)[0], (v1)[1]), pk2((v1)[2], (v1)[3])}
;     __device__ __forceinline__ void operator()(AccRef acc, const Unit& u, int wr, int wc, int fr, int fq) const {
;     ...
;         for (int bj = 0; bj < 2; ++bj) { const size_t p = (size_t)EPI_IT_ROW(0) * DM + EPI_COL(bj); xc[bj][0] = *(const f32x4*)(xin + p); xc[bj][1] = *(const f32x4*)(xin + p + 4); }
; #pragma unroll
;         for (int it = 0; it < 8; ++it) { const int ai = it >> 2, m = it & 3, row = EPI_IT_ROW(it);
;             if (it + 1 < 8) {
; #pragma unroll
;                 for (int bj = 0; bj < 2; ++bj) { const size_t p = (size_t)EPI_IT_ROW(it + 1) * DM + EPI_COL(bj); xn[bj][0] = *(const f32x4*)(xin + p); xn[bj][1] = *(const f32x4*)(xin + p + 4); } }
;             float q = 0.f;
; #pragma unroll
;             for (int bj = 0; bj < 2; ++bj) { const size_t p = (size_t)row * DM + EPI_COL(bj);
;                 const f32x4 x0 = xc[bj][0] + acc[ai][bj][m][0], x1 = xc[bj][1] + acc[ai][bj][m][1];
;                 __builtin_nontemporal_store(x0, (f32x4*)(xout + p)); __builtin_nontemporal_store(x1, (f32x4*)(xout + p + 4));
;                 *(u32x4*)(xb + p) = EPI_PACK8(x0, x1);
;                 q += EPI_SQ8(x0, x1); }
;             q += __shfl_xor(q, 16); q += __shfl_xor(q, 32);
;             if (fq == 0) atomicAdd(ssout + row, q);
; #pragma unroll
;             for (int bj = 0; bj < 2; ++bj) { xc[bj][0] = xn[bj][0]; xc[bj][1] = xn[bj][1]; } }
.LBB0_1327:
	s_or_b64 exec, exec, s[0:1]
	s_waitcnt vmcnt(16)
	v_mov_b64_e32 v[72:73], v[228:229]
	v_mov_b64_e32 v[74:75], v[230:231]
	v_mov_b64_e32 v[76:77], v[232:233]
	v_mov_b64_e32 v[78:79], v[234:235]
	v_mov_b64_e32 v[64:65], v[236:237]
	v_mov_b64_e32 v[66:67], v[238:239]
	v_mov_b64_e32 v[68:69], v[240:241]
	v_mov_b64_e32 v[70:71], v[242:243]
	v_add_u32_e32 v244, 176, v164
	v_ashrrev_i32_e32 v245, 31, v244
	v_lshlrev_b64 v[246:247], 12, v[244:245]
	v_lshl_add_u64 v[246:247], s[48:49], 0, v[246:247]
	v_lshl_add_u64 v[248:249], v[162:163], 2, v[246:247]
	v_lshl_add_u64 v[250:251], v[160:161], 2, v[246:247]
	global_load_dwordx4 v[228:231], v[248:249], off offset:16
	global_load_dwordx4 v[232:235], v[248:249], off
	global_load_dwordx4 v[236:239], v[250:251], off offset:16
	global_load_dwordx4 v[240:243], v[250:251], off
	v_add_u32_e32 v80, 0xa0, v164
	v_ashrrev_i32_e32 v81, 31, v80
	s_waitcnt lgkmcnt(0)
	v_lshlrev_b64 v[48:49], 12, v[80:81]
	v_lshl_add_u64 v[48:49], s[48:49], 0, v[48:49]
	v_lshl_add_u64 v[84:85], v[162:163], 2, v[48:49]
	v_lshl_add_u64 v[82:83], v[160:161], 2, v[48:49]
	v_pk_add_f32 v[46:47], v[46:47], v[78:79]
	v_pk_add_f32 v[44:45], v[44:45], v[76:77]
	v_pk_add_f32 v[42:43], v[42:43], v[74:75]
	v_pk_add_f32 v[40:41], v[40:41], v[72:73]
	global_store_dwordx4 v[100:101], v[44:47], off nt
	global_store_dwordx4 v[100:101], v[40:43], off offset:16 nt
	v_cvt_pk_bf16_f32 v72, v44, v45
	v_cvt_pk_bf16_f32 v74, v40, v41
	v_pk_add_f32 v[38:39], v[38:39], v[70:71]
	v_mul_f32_e32 v45, v45, v45
	v_fmac_f32_e32 v45, v44, v44
	v_mul_f32_e32 v44, v47, v47
	v_fmac_f32_e32 v44, v46, v46
	v_mul_f32_e32 v41, v41, v41
	v_add_f32_e32 v44, v45, v44
	v_fmac_f32_e32 v41, v40, v40
	v_add_f32_e32 v40, v44, v41
	v_mul_f32_e32 v41, v43, v43
	v_fmac_f32_e32 v41, v42, v42
	v_pk_add_f32 v[36:37], v[36:37], v[68:69]
	v_cvt_pk_bf16_f32 v73, v46, v47
	v_add_f32_e32 v46, v41, v40
	v_pk_add_f32 v[40:41], v[32:33], v[64:65]
	v_mul_f32_e32 v32, v37, v37
	v_mul_f32_e32 v33, v39, v39
	v_fmac_f32_e32 v32, v36, v36
	v_fmac_f32_e32 v33, v38, v38
	v_add_f32_e32 v32, v32, v33
	v_mul_f32_e32 v33, v41, v41
	v_cvt_pk_bf16_f32 v75, v42, v43
	v_pk_add_f32 v[42:43], v[34:35], v[66:67]
	v_fmac_f32_e32 v33, v40, v40
	v_add_f32_e32 v32, v32, v33
	v_mul_f32_e32 v33, v43, v43
	v_fmac_f32_e32 v33, v42, v42
	v_add_f32_e32 v32, v33, v32
	v_add_f32_e32 v32, v46, v32
	v_mov_b32_e32 v33, v32
	s_nop 1
	v_permlane16_swap_b32_e32 v33, v32
	v_lshlrev_b64 v[86:87], 10, v[96:97]
	v_lshl_add_u64 v[88:89], v[86:87], 0, v[162:163]
	v_lshl_add_u64 v[76:77], v[88:89], 1, s[24:25]
	v_lshl_add_u64 v[44:45], v[86:87], 0, v[160:161]
	s_waitcnt lgkmcnt(0)
	v_add_f32_e32 v32, v32, v33
	v_mov_b32_e32 v33, v32
	s_nop 1
	v_permlane32_swap_b32_e32 v33, v32
	global_store_dwordx4 v[76:77], v[72:75], off
	global_store_dwordx4 v[98:99], v[36:39], off nt
	global_store_dwordx4 v[98:99], v[40:43], off offset:16 nt
	v_cvt_pk_bf16_f32 v35, v38, v39
	v_cvt_pk_bf16_f32 v34, v36, v37
	s_nop 0
	v_lshl_add_u64 v[38:39], v[44:45], 1, s[24:25]
	v_cvt_pk_bf16_f32 v36, v40, v41
	v_cvt_pk_bf16_f32 v37, v42, v43
	global_store_dwordx4 v[38:39], v[34:37], off
	s_and_saveexec_b64 s[0:1], vcc
	s_cbranch_execz .LBB0_1329
	v_lshl_add_u64 v[34:35], v[96:97], 2, s[10:11]
	s_waitcnt lgkmcnt(0)
	v_add_f32_e32 v32, v32, v33
	global_atomic_add_f32 v[34:35], v32, off
; #define EPI_IT_ROW(it) EPI_ROW((it) >> 2, (it) & 3)
; #define EPI_PACK8(v0, v1) (u32x4){pk2((v0)[0], (v0)[1]), pk2((v0)[2], (v0)[3]), pk2((v1)[0], (v1)[1]), pk2((v1)[2], (v1)[3])}
;     __device__ __forceinline__ void operator()(AccRef acc, const Unit& u, int wr, int wc, int fr, int fq) const {
;     ...
;         for (int bj = 0; bj < 2; ++bj) { const size_t p = (size_t)EPI_IT_ROW(0) * DM + EPI_COL(bj); xc[bj][0] = *(const f32x4*)(xin + p); xc[bj][1] = *(const f32x4*)(xin + p + 4); }
; #pragma unroll
;         for (int it = 0; it < 8; ++it) { const int ai = it >> 2, m = it & 3, row = EPI_IT_ROW(it);
;             if (it + 1 < 8) {
; #pragma unroll
;                 for (int bj = 0; bj < 2; ++bj) { const size_t p = (size_t)EPI_IT_ROW(it + 1) * DM + EPI_COL(bj); xn[bj][0] = *(const f32x4*)(xin + p); xn[bj][1] = *(const f32x4*)(xin + p + 4); } }
;             float q = 0.f;
; #pragma unroll
;             for (int bj = 0; bj < 2; ++bj) { const size_t p = (size_t)row * DM + EPI_COL(bj);
;                 const f32x4 x0 = xc[bj][0] + acc[ai][bj][m][0], x1 = xc[bj][1] + acc[ai][bj][m][1];
;                 __builtin_nontemporal_store(x0, (f32x4*)(xout + p)); __builtin_nontemporal_store(x1, (f32x4*)(xout + p + 4));
;                 *(u32x4*)(xb + p) = EPI_PACK8(x0, x1);
;                 q += EPI_SQ8(x0, x1); }
;             q += __shfl_xor(q, 16); q += __shfl_xor(q, 32);
;             if (fq == 0) atomicAdd(ssout + row, q);
; #pragma unroll
;             for (int bj = 0; bj < 2; ++bj) { xc[bj][0] = xn[bj][0]; xc[bj][1] = xn[bj][1]; } }
.LBB0_1329:
	s_or_b64 exec, exec, s[0:1]
	s_waitcnt vmcnt(16)
	v_mov_b64_e32 v[56:57], v[206:207]
	v_mov_b64_e32 v[58:59], v[208:209]
	v_mov_b64_e32 v[60:61], v[210:211]
	v_mov_b64_e32 v[62:63], v[212:213]
	v_mov_b64_e32 v[48:49], v[214:215]
	v_mov_b64_e32 v[50:51], v[216:217]
	v_mov_b64_e32 v[52:53], v[218:219]
	v_mov_b64_e32 v[54:55], v[220:221]
	v_add_u32_e32 v64, 0xb0, v164
	v_ashrrev_i32_e32 v65, 31, v64
	s_waitcnt lgkmcnt(0)
	v_lshlrev_b64 v[32:33], 12, v[64:65]
	v_lshl_add_u64 v[32:33], s[48:49], 0, v[32:33]
	v_lshl_add_u64 v[68:69], v[162:163], 2, v[32:33]
	v_lshl_add_u64 v[66:67], v[160:161], 2, v[32:33]
	v_pk_add_f32 v[30:31], v[30:31], v[62:63]
	v_pk_add_f32 v[28:29], v[28:29], v[60:61]
	v_pk_add_f32 v[26:27], v[26:27], v[58:59]
	v_pk_add_f32 v[24:25], v[24:25], v[56:57]
	global_store_dwordx4 v[84:85], v[28:31], off nt
	global_store_dwordx4 v[84:85], v[24:27], off offset:16 nt
	v_cvt_pk_bf16_f32 v56, v28, v29
	v_cvt_pk_bf16_f32 v58, v24, v25
	v_pk_add_f32 v[22:23], v[22:23], v[54:55]
	v_mul_f32_e32 v29, v29, v29
	v_fmac_f32_e32 v29, v28, v28
	v_mul_f32_e32 v28, v31, v31
	v_fmac_f32_e32 v28, v30, v30
	v_mul_f32_e32 v25, v25, v25
	v_add_f32_e32 v28, v29, v28
	v_fmac_f32_e32 v25, v24, v24
	v_add_f32_e32 v24, v28, v25
	v_mul_f32_e32 v25, v27, v27
	v_fmac_f32_e32 v25, v26, v26
	v_pk_add_f32 v[20:21], v[20:21], v[52:53]
	v_cvt_pk_bf16_f32 v57, v30, v31
	v_add_f32_e32 v30, v25, v24
	v_pk_add_f32 v[24:25], v[16:17], v[48:49]
	v_mul_f32_e32 v16, v21, v21
	v_mul_f32_e32 v17, v23, v23
	v_fmac_f32_e32 v16, v20, v20
	v_fmac_f32_e32 v17, v22, v22
	v_add_f32_e32 v16, v16, v17
	v_mul_f32_e32 v17, v25, v25
	v_cvt_pk_bf16_f32 v59, v26, v27
	v_pk_add_f32 v[26:27], v[18:19], v[50:51]
	v_fmac_f32_e32 v17, v24, v24
	v_add_f32_e32 v16, v16, v17
	v_mul_f32_e32 v17, v27, v27
	v_fmac_f32_e32 v17, v26, v26
	v_add_f32_e32 v16, v17, v16
	v_add_f32_e32 v16, v30, v16
	v_mov_b32_e32 v17, v16
	s_nop 1
	v_permlane16_swap_b32_e32 v17, v16
	v_lshlrev_b64 v[70:71], 10, v[80:81]
	v_lshl_add_u64 v[72:73], v[70:71], 0, v[162:163]
	v_lshl_add_u64 v[60:61], v[72:73], 1, s[24:25]
	v_lshl_add_u64 v[28:29], v[70:71], 0, v[160:161]
	s_waitcnt lgkmcnt(0)
	v_add_f32_e32 v16, v16, v17
	v_mov_b32_e32 v17, v16
	s_nop 1
	v_permlane32_swap_b32_e32 v17, v16
	global_store_dwordx4 v[60:61], v[56:59], off
	global_store_dwordx4 v[82:83], v[20:23], off nt
	global_store_dwordx4 v[82:83], v[24:27], off offset:16 nt
	v_cvt_pk_bf16_f32 v19, v22, v23
	v_cvt_pk_bf16_f32 v18, v20, v21
	s_nop 0
	v_lshl_add_u64 v[22:23], v[28:29], 1, s[24:25]
	v_cvt_pk_bf16_f32 v20, v24, v25
	v_cvt_pk_bf16_f32 v21, v26, v27
	global_store_dwordx4 v[22:23], v[18:21], off
	s_and_saveexec_b64 s[0:1], vcc
	s_cbranch_execz .LBB0_1331
	v_lshl_add_u64 v[18:19], v[80:81], 2, s[10:11]
	s_waitcnt lgkmcnt(0)
	v_add_f32_e32 v16, v16, v17
	global_atomic_add_f32 v[18:19], v16, off
.LBB0_1331:
	s_or_b64 exec, exec, s[0:1]
	s_waitcnt vmcnt(12)
	v_mov_b64_e32 v[40:41], v[228:229]
	v_mov_b64_e32 v[42:43], v[230:231]
	v_mov_b64_e32 v[44:45], v[232:233]
	v_mov_b64_e32 v[46:47], v[234:235]
	v_mov_b64_e32 v[32:33], v[236:237]
	v_mov_b64_e32 v[34:35], v[238:239]
	v_mov_b64_e32 v[36:37], v[240:241]
	v_mov_b64_e32 v[38:39], v[242:243]
	v_pk_add_f32 v[14:15], v[14:15], v[46:47]
	v_pk_add_f32 v[12:13], v[12:13], v[44:45]
	v_pk_add_f32 v[10:11], v[10:11], v[42:43]
	v_pk_add_f32 v[8:9], v[8:9], v[40:41]
	global_store_dwordx4 v[68:69], v[12:15], off nt
	global_store_dwordx4 v[68:69], v[8:11], off offset:16 nt
	v_cvt_pk_bf16_f32 v16, v12, v13
	v_cvt_pk_bf16_f32 v18, v8, v9
	v_pk_add_f32 v[6:7], v[6:7], v[38:39]
	v_mul_f32_e32 v13, v13, v13
	v_fmac_f32_e32 v13, v12, v12
	v_mul_f32_e32 v12, v15, v15
	v_fmac_f32_e32 v12, v14, v14
	v_mul_f32_e32 v9, v9, v9
	v_add_f32_e32 v12, v13, v12
	v_fmac_f32_e32 v9, v8, v8
	v_add_f32_e32 v8, v12, v9
	v_mul_f32_e32 v9, v11, v11
	v_fmac_f32_e32 v9, v10, v10
	v_pk_add_f32 v[4:5], v[4:5], v[36:37]
	s_waitcnt lgkmcnt(0)
	v_cvt_pk_bf16_f32 v17, v14, v15
	v_add_f32_e32 v14, v9, v8
	v_pk_add_f32 v[8:9], v[0:1], v[32:33]
	v_mul_f32_e32 v0, v5, v5
	v_mul_f32_e32 v1, v7, v7
	v_fmac_f32_e32 v0, v4, v4
	v_fmac_f32_e32 v1, v6, v6
	v_add_f32_e32 v0, v0, v1
	v_mul_f32_e32 v1, v9, v9
	v_cvt_pk_bf16_f32 v19, v10, v11
	v_pk_add_f32 v[10:11], v[2:3], v[34:35]
	v_fmac_f32_e32 v1, v8, v8
	v_add_f32_e32 v0, v0, v1
	v_mul_f32_e32 v1, v11, v11
	v_fmac_f32_e32 v1, v10, v10
	v_add_f32_e32 v0, v1, v0
	v_add_f32_e32 v0, v14, v0
	v_mov_b32_e32 v1, v0
	s_nop 1
	v_permlane16_swap_b32_e32 v1, v0
	v_lshlrev_b64 v[20:21], 10, v[64:65]
	v_lshl_add_u64 v[22:23], v[20:21], 0, v[162:163]
	v_lshl_add_u64 v[22:23], v[22:23], 1, s[24:25]
	v_lshl_add_u64 v[12:13], v[20:21], 0, v[160:161]
	s_waitcnt lgkmcnt(0)
	v_add_f32_e32 v0, v0, v1
	v_mov_b32_e32 v1, v0
	s_nop 1
	v_permlane32_swap_b32_e32 v1, v0
	global_store_dwordx4 v[22:23], v[16:19], off
	global_store_dwordx4 v[66:67], v[4:7], off nt
	global_store_dwordx4 v[66:67], v[8:11], off offset:16 nt
	v_cvt_pk_bf16_f32 v3, v6, v7
	v_cvt_pk_bf16_f32 v2, v4, v5
	s_nop 0
	v_lshl_add_u64 v[6:7], v[12:13], 1, s[24:25]
	v_cvt_pk_bf16_f32 v4, v8, v9
	v_cvt_pk_bf16_f32 v5, v10, v11
	global_store_dwordx4 v[6:7], v[2:5], off
	s_and_saveexec_b64 s[0:1], vcc
	s_cbranch_execz .LBB0_1333
	v_lshl_add_u64 v[2:3], v[64:65], 2, s[10:11]
	s_waitcnt lgkmcnt(0)
	v_add_f32_e32 v0, v0, v1
	global_atomic_add_f32 v[2:3], v0, off

; #define EPI_IT_ROW(it) EPI_ROW((it) >> 2, (it) & 3)
; #define EPI_PACK8(v0, v1) (u32x4){pk2((v0)[0], (v0)[1]), pk2((v0)[2], (v0)[3]), pk2((v1)[0], (v1)[1]), pk2((v1)[2], (v1)[3])}
;     __device__ __forceinline__ void operator()(AccRef acc, const Unit& u, int wr, int wc, int fr, int fq) const {
;     ...
;         f32x4 xc[2][2], xn[2][2];
; #pragma unroll
;         for (int bj = 0; bj < 2; ++bj) { const size_t p = (size_t)EPI_IT_ROW(0) * DM + EPI_COL(bj); xc[bj][0] = *(const f32x4*)(xin + p); xc[bj][1] = *(const f32x4*)(xin + p + 4); }
; #pragma unroll
;         for (int it = 0; it < 8; ++it) { const int ai = it >> 2, m = it & 3, row = EPI_IT_ROW(it);
;             if (it + 1 < 8) {
; #pragma unroll
;                 for (int bj = 0; bj < 2; ++bj) { const size_t p = (size_t)EPI_IT_ROW(it + 1) * DM + EPI_COL(bj); xn[bj][0] = *(const f32x4*)(xin + p); xn[bj][1] = *(const f32x4*)(xin + p + 4); } }
;             float q = 0.f;
; #pragma unroll
;             for (int bj = 0; bj < 2; ++bj) { const size_t p = (size_t)row * DM + EPI_COL(bj);
;                 const f32x4 x0 = xc[bj][0] + acc[ai][bj][m][0], x1 = xc[bj][1] + acc[ai][bj][m][1];
;                 __builtin_nontemporal_store(x0, (f32x4*)(xout + p)); __builtin_nontemporal_store(x1, (f32x4*)(xout + p + 4));
;                 *(u32x4*)(xb + p) = EPI_PACK8(x0, x1);
;                 q += EPI_SQ8(x0, x1); }
;             q += __shfl_xor(q, 16); q += __shfl_xor(q, 32);
;             if (fq == 0) atomicAdd(ssout + row, q);
; #pragma unroll
;             for (int bj = 0; bj < 2; ++bj) { xc[bj][0] = xn[bj][0]; xc[bj][1] = xn[bj][1]; } }
.LBB0_1652:
	s_lshl_b32 s0, s60, 8
	v_mov_b32_e32 v128, v180
	v_mov_b32_e32 v186, v177
	s_add_i32 s0, s0, s38
	v_and_b32_e32 v202, 64, v185
	v_add_u32_e32 v164, s0, v128
	s_lshl_b32 s0, s59, 8
	s_or_b32 s0, s0, s39
	v_ashrrev_i32_e32 v165, 31, v164
	v_lshl_add_u32 v162, v186, 3, s0
	v_lshlrev_b64 v[128:129], 12, v[164:165]
	v_ashrrev_i32_e32 v163, 31, v162
	v_add_u32_e32 v160, 0x80, v162
	v_lshl_add_u64 v[128:129], s[48:49], 0, v[128:129]
	v_lshlrev_b64 v[130:131], 2, v[162:163]
	v_ashrrev_i32_e32 v161, 31, v160
	v_lshl_add_u64 v[178:179], v[128:129], 0, v[130:131]
	v_lshlrev_b64 v[132:133], 2, v[160:161]
	global_load_dwordx4 v[170:173], v[178:179], off offset:16
	global_load_dwordx4 v[188:191], v[178:179], off
	v_lshl_add_u64 v[200:201], v[128:129], 0, v[132:133]
	global_load_dwordx4 v[192:195], v[200:201], off
	global_load_dwordx4 v[196:199], v[200:201], off offset:16
	v_add_u32_e32 v166, 16, v164
	v_ashrrev_i32_e32 v167, 31, v166
	v_lshlrev_b64 v[128:129], 12, v[166:167]
	v_lshl_add_u64 v[128:129], s[48:49], 0, v[128:129]
	v_lshl_add_u64 v[174:175], v[128:129], 0, v[130:131]
	v_lshl_add_u64 v[168:169], v[128:129], 0, v[132:133]
	global_load_dwordx4 v[136:139], v[174:175], off offset:16
	global_load_dwordx4 v[140:143], v[174:175], off
	global_load_dwordx4 v[128:131], v[168:169], off offset:16
	global_load_dwordx4 v[132:135], v[168:169], off
	v_add_u32_e32 v244, 32, v164
	v_ashrrev_i32_e32 v245, 31, v244
	v_lshlrev_b64 v[246:247], 12, v[244:245]
	v_lshl_add_u64 v[246:247], s[48:49], 0, v[246:247]
	v_lshl_add_u64 v[248:249], v[162:163], 2, v[246:247]
	v_lshl_add_u64 v[250:251], v[160:161], 2, v[246:247]
	global_load_dwordx4 v[206:209], v[248:249], off offset:16
	global_load_dwordx4 v[210:213], v[248:249], off
	global_load_dwordx4 v[214:217], v[250:251], off offset:16
	global_load_dwordx4 v[218:221], v[250:251], off
	v_add_u32_e32 v244, 48, v164
	v_ashrrev_i32_e32 v245, 31, v244
	v_lshlrev_b64 v[246:247], 12, v[244:245]
	v_lshl_add_u64 v[246:247], s[48:49], 0, v[246:247]
	v_lshl_add_u64 v[248:249], v[162:163], 2, v[246:247]
	v_lshl_add_u64 v[250:251], v[160:161], 2, v[246:247]
	global_load_dwordx4 v[228:231], v[248:249], off offset:16
	global_load_dwordx4 v[232:235], v[248:249], off
	global_load_dwordx4 v[236:239], v[250:251], off offset:16
	global_load_dwordx4 v[240:243], v[250:251], off
	v_xor_b32_e32 v187, 16, v185
	v_add_u32_e32 v202, 64, v202
	v_cmp_lt_i32_e64 s[0:1], v187, v202
	v_cmp_eq_u32_e32 vcc, 0, v186
	v_xor_b32_e32 v203, 32, v185
	v_cndmask_b32_e64 v186, v185, v187, s[0:1]
	v_lshlrev_b32_e32 v186, 2, v186
	v_cmp_lt_i32_e64 s[0:1], v203, v202
	s_waitcnt vmcnt(8)
	v_pk_add_f32 v[122:123], v[122:123], v[172:173]
	v_pk_add_f32 v[126:127], v[126:127], v[190:191]
	v_pk_add_f32 v[124:125], v[124:125], v[188:189]
	v_pk_add_f32 v[118:119], v[118:119], v[194:195]
	v_pk_add_f32 v[116:117], v[116:117], v[192:193]
	v_pk_add_f32 v[120:121], v[120:121], v[170:171]
	v_pk_add_f32 v[170:171], v[112:113], v[196:197]
	global_store_dwordx4 v[178:179], v[124:127], off nt
	global_store_dwordx4 v[178:179], v[120:123], off offset:16 nt
	v_cvt_pk_bf16_f32 v112, v124, v125
	v_cvt_pk_bf16_f32 v113, v126, v127
	v_mul_f32_e32 v178, v117, v117
	v_mul_f32_e32 v125, v125, v125
	v_mul_f32_e32 v127, v127, v127
	v_mul_f32_e32 v179, v119, v119
	v_pk_add_f32 v[172:173], v[114:115], v[198:199]
	v_cvt_pk_bf16_f32 v114, v120, v121
	v_cvt_pk_bf16_f32 v115, v122, v123
	v_mul_f32_e32 v121, v121, v121
	v_mul_f32_e32 v123, v123, v123
	v_mul_f32_e32 v189, v171, v171
	v_fmac_f32_e32 v125, v124, v124
	v_fmac_f32_e32 v127, v126, v126
	v_fmac_f32_e32 v178, v116, v116
	v_fmac_f32_e32 v179, v118, v118
	v_mul_f32_e32 v190, v173, v173
	v_fmac_f32_e32 v121, v120, v120
	v_fmac_f32_e32 v123, v122, v122
	v_fmac_f32_e32 v189, v170, v170
	v_add_f32_e32 v120, v125, v127
	v_add_f32_e32 v122, v178, v179
	v_fmac_f32_e32 v190, v172, v172
	v_add_f32_e32 v120, v120, v121
	v_add_f32_e32 v121, v122, v189
	v_add_f32_e32 v120, v123, v120
	v_add_f32_e32 v121, v190, v121
	v_add_f32_e32 v120, v120, v121
	v_mov_b32_e32 v121, v120
	s_nop 1
	v_permlane16_swap_b32_e32 v121, v120
	v_cndmask_b32_e64 v187, v185, v203, s[0:1]
	v_lshlrev_b64 v[202:203], 10, v[164:165]
	v_lshl_add_u64 v[204:205], v[202:203], 0, v[162:163]
	v_lshl_add_u64 v[204:205], v[204:205], 1, s[30:31]
	global_store_dwordx4 v[204:205], v[112:115], off
	global_store_dwordx4 v[200:201], v[116:119], off nt
	global_store_dwordx4 v[200:201], v[170:173], off offset:16 nt
	s_waitcnt lgkmcnt(0)
	v_add_f32_e32 v112, v120, v121
	v_lshlrev_b32_e32 v187, 2, v187
	v_mov_b32_e32 v113, v112
	s_nop 1
	v_permlane32_swap_b32_e32 v113, v112
	v_lshl_add_u64 v[202:203], v[202:203], 0, v[160:161]
	v_lshl_add_u64 v[114:115], v[202:203], 1, s[30:31]
	v_cvt_pk_bf16_f32 v188, v116, v117
	v_cvt_pk_bf16_f32 v189, v118, v119
	v_cvt_pk_bf16_f32 v190, v170, v171
	v_cvt_pk_bf16_f32 v191, v172, v173
	global_store_dwordx4 v[114:115], v[188:191], off
	s_and_saveexec_b64 s[0:1], vcc
	s_cbranch_execz .LBB0_1654
	v_lshl_add_u64 v[114:115], v[164:165], 2, s[12:13]
	s_waitcnt lgkmcnt(0)
	v_add_f32_e32 v112, v112, v113
	global_atomic_add_f32 v[114:115], v112, off
